# SSM v5: two batches per wave (one per half-wave), no cross-lane ops, plain fmac recurrence, natural-k LDS layout
# baseline (speedup 1.0000x reference)
.LBB0_340:
	s_cmp_lt_i32 s96, 4
	s_cselect_b64 s[0:1], -1, 0
	s_and_b64 s[8:9], s[0:1], s[4:5]
	s_andn2_b64 vcc, exec, s[8:9]
	s_cbranch_vccnz .LBB0_393
	v_cmp_gt_u32_e32 vcc, 2, v190
	s_and_saveexec_b64 s[0:1], vcc
	v_lshlrev_b32_e32 v2, 2, v190
	v_add_u32_e32 v2, 0x21000, v2
	v_mov_b32_e32 v3, 0
	ds_write_b32 v2, v3
	s_mov_b64 exec, s[0:1]
	s_mul_i32 s20, s89, 0x2200
	s_waitcnt vmcnt(0) lgkmcnt(0)
	s_barrier
	s_and_b32 s22, s89, 2
	s_cmp_lg_u32 s22, 0
	s_cbranch_scc1 .Lssm_ctx
	s_and_b32 s22, s2, 7
	s_and_b32 s23, s22, 3
	s_lshl_b32 s23, s23, 1
	s_lshr_b32 s24, s22, 2
	s_lshl_b32 s24, s24, 5
	s_lshr_b32 s26, s2, 3
	s_add_u32 s24, s24, s26
	s_lshl_b32 s25, s23, 10
	s_add_u32 s25, s25, 0x2000
	s_cmp_ge_u32 s89, 4
	s_cbranch_scc1 .Lssm_spin_pre
	s_cmp_eq_u32 s89, 0
	s_cbranch_scc0 .Lssm_lat_bwd
	v_and_b32_e32 v6, 31, v191
	v_lshrrev_b32_e32 v7, 5, v191
	v_and_b32_e32 v8, 15, v191
	v_lshrrev_b32_e32 v9, 4, v191
	v_lshrrev_b32_e32 v10, 3, v6
	v_lshlrev_b32_e32 v10, 10, v10
	v_and_b32_e32 v11, 7, v6
	v_lshl_add_u32 v10, v11, 5, v10
	v_lshl_add_u32 v10, v7, 8, v10
	s_add_u32 s28, s24, 0
	s_lshl_b32 s29, s28, 13
	s_add_u32 s29, s29, 0x200000
	s_add_u32 s10, s62, s29
	s_addc_u32 s11, s63, 0
	s_add_u32 s12, s10, 0x1000
	s_addc_u32 s13, s11, 0
	global_load_dwordx4 v[88:91], v10, s[10:11]
	global_load_dwordx4 v[92:95], v10, s[10:11] offset:16
	global_load_dwordx4 v[96:99], v10, s[12:13]
	global_load_dwordx4 v[100:103], v10, s[12:13] offset:16
	s_lshl_b32 s29, s28, 12
	s_add_u32 s29, s29, 0x300000
	s_add_u32 s16, s62, s29
	s_addc_u32 s17, s63, 0
	v_lshlrev_b32_e32 v10, 4, v191
	global_load_dwordx4 v[104:107], v10, s[16:17]
	global_load_dwordx4 v[108:111], v10, s[16:17] offset:1024
	global_load_dwordx4 v[112:115], v10, s[16:17] offset:2048
	global_load_dwordx4 v[116:119], v10, s[16:17] offset:3072
	s_lshl_b32 s29, s28, 9
	s_add_u32 s29, s29, 0x100000
	s_add_u32 s18, s62, s29
	s_addc_u32 s19, s63, 0
	v_lshlrev_b32_e32 v10, 3, v6
	global_load_dwordx2 v[120:121], v10, s[18:19]
	global_load_dwordx2 v[122:123], v10, s[18:19] offset:256
	s_lshl_b32 s30, s23, 1
	s_lshl_b32 s30, s30, 15
	s_lshl_b32 s31, s24, 8
	s_add_u32 s30, s30, s31
	v_lshlrev_b32_e32 v10, 16, v7
	v_lshl_add_u32 v10, v6, 2, v10
	v_mov_b32_e32 v196, v10
	v_readlane_b32 s34, v254, 10
	v_readlane_b32 s35, v254, 11
	s_nop 3
	s_add_u32 s34, s34, s30
	s_addc_u32 s35, s35, 0
	s_add_u32 s38, s34, 0x4000
	s_addc_u32 s39, s35, 0
	global_load_dword v126, v10, s[34:35]
	global_load_dword v128, v10, s[34:35] offset:128
	global_load_dword v127, v10, s[38:39]
	global_load_dword v129, v10, s[38:39] offset:128
	s_mul_i32 s31, s25, 0x1800
	s_lshl_b32 s29, s24, 5
	s_add_u32 s31, s31, s29
	s_add_u32 s31, s31, 0x8801000
	s_add_u32 s4, s62, s31
	s_addc_u32 s5, s63, 0
	v_lshrrev_b32_e32 v10, 3, v6
	v_and_b32_e32 v11, 3, v6
	v_lshl_add_u32 v10, v10, 2, v11
	v_mul_u32_u24_e32 v10, 0x1800, v10
	v_lshl_add_u32 v10, v7, 4, v10
	v_bfe_u32 v11, v6, 2, 1
	v_mul_u32_u24_e32 v11, 6291456, v11
	v_add_u32_e32 v186, v10, v11
	v_mul_u32_u24_e32 v10, 0x1100, v7
	v_lshl_add_u32 v10, v6, 2, v10
	v_add_u32_e32 v14, s20, v10
	v_add_u32_e32 v15, 1088, v14
	v_add_u32_e32 v184, 2176, v14
	v_add_u32_e32 v185, 3264, v14
	v_mul_u32_u24_e32 v10, 0x110, v8
	v_lshl_add_u32 v10, v9, 4, v10
	v_add_u32_e32 v187, s20, v10
	v_lshlrev_b32_e32 v10, 12, v8
	v_lshl_add_u32 v188, v9, 4, v10
	v_add_u32_e32 v189, 0x400000, v188
	s_lshl_b32 s31, s25, 12
	s_lshl_b32 s29, s24, 6
	s_add_u32 s31, s31, s29
	s_add_u32 s6, s60, s31
	s_addc_u32 s7, s61, 0
	s_add_u32 s34, s4, 0
	s_addc_u32 s35, s5, 0
	global_load_dwordx4 v[80:83], v186, s[34:35]
	s_mov_b64 s[10:11], s[34:35]
	s_add_u32 s10, s10, 98304
	s_addc_u32 s11, s11, 0
	global_load_dwordx4 v[84:87], v186, s[10:11]
	s_mov_b64 s[34:35], s[10:11]
	s_add_u32 s10, s10, 98304
	s_addc_u32 s11, s11, 0
	s_add_u32 s12, s6, 0
	s_addc_u32 s13, s7, 0
	s_mov_b32 s14, 0
	s_waitcnt vmcnt(0)
	v_xor_b32_e32 v124, 0x80000000, v121
	v_xor_b32_e32 v125, 0x80000000, v123
.Lssm_tile_d0m0:
	s_cmp_eq_u32 s14, 0
	s_cbranch_scc1 .Lssm_sk1_d0m0
	ds_read_b128 v[130:133], v187
	ds_read_b128 v[134:137], v187 offset:64
	ds_read_b128 v[138:141], v187 offset:128
	ds_read_b128 v[142:145], v187 offset:192
	ds_read_b128 v[146:149], v187 offset:4352
	ds_read_b128 v[150:153], v187 offset:4416
	ds_read_b128 v[154:157], v187 offset:4480
	ds_read_b128 v[158:161], v187 offset:4544
.Lssm_sk1_d0m0:
	s_waitcnt vmcnt(3)
	v_mfma_f32_32x32x16_bf16 v[16:31], v[80:83], v[88:91], 0
	v_mfma_f32_32x32x16_bf16 v[32:47], v[80:83], v[92:95], 0
	v_mfma_f32_32x32x16_bf16 v[48:63], v[80:83], v[96:99], 0
	v_mfma_f32_32x32x16_bf16 v[64:79], v[80:83], v[100:103], 0
	s_cmp_eq_u32 s14, 0
	s_cbranch_scc1 .Lssm_sk3_d0m0
	s_waitcnt lgkmcnt(0)
	v_mfma_f32_16x16x32_bf16 v[162:165], v[104:107], v[130:133], 0
	v_mfma_f32_16x16x32_bf16 v[166:169], v[104:107], v[146:149], 0
	v_mfma_f32_16x16x32_bf16 v[162:165], v[108:111], v[134:137], v[162:165]
	v_mfma_f32_16x16x32_bf16 v[166:169], v[108:111], v[150:153], v[166:169]
	v_mfma_f32_16x16x32_bf16 v[162:165], v[112:115], v[138:141], v[162:165]
	v_mfma_f32_16x16x32_bf16 v[166:169], v[112:115], v[154:157], v[166:169]
	v_mfma_f32_16x16x32_bf16 v[162:165], v[116:119], v[142:145], v[162:165]
	v_mfma_f32_16x16x32_bf16 v[166:169], v[116:119], v[158:161], v[166:169]
	s_nop 7
	global_store_dwordx4 v188, v[162:165], s[12:13]
	global_store_dwordx4 v189, v[166:169], s[12:13]
	s_add_u32 s12, s12, 65536
	s_addc_u32 s13, s13, 0
.Lssm_sk3_d0m0:
	s_nop 9
	global_load_dwordx4 v[80:83], v186, s[10:11]
	s_add_u32 s34, s34, 98304
	s_addc_u32 s35, s35, 0
	s_add_u32 s10, s10, 98304
	s_addc_u32 s11, s11, 0
	v_fmac_f32_e32 v16, v120, v126
	v_fmac_f32_e32 v32, v120, v127
	v_fmac_f32_e32 v48, v122, v128
	v_fmac_f32_e32 v64, v122, v129
	v_fmac_f32_e32 v16, v124, v127
	v_fmac_f32_e32 v32, v121, v126
	v_fmac_f32_e32 v48, v125, v129
	v_fmac_f32_e32 v64, v123, v128
	v_cvt_pk_bf16_f32 v170, v16, v32
	v_cvt_pk_bf16_f32 v171, v48, v64
	ds_write2_b32 v14, v170, v171 offset1:32
	v_fmac_f32_e32 v17, v120, v16
	v_fmac_f32_e32 v33, v120, v32
	v_fmac_f32_e32 v49, v122, v48
	v_fmac_f32_e32 v65, v122, v64
	v_fmac_f32_e32 v17, v124, v32
	v_fmac_f32_e32 v33, v121, v16
	v_fmac_f32_e32 v49, v125, v64
	v_fmac_f32_e32 v65, v123, v48
	v_cvt_pk_bf16_f32 v170, v17, v33
	v_cvt_pk_bf16_f32 v171, v49, v65
	ds_write2_b32 v14, v170, v171 offset0:68 offset1:100
	v_fmac_f32_e32 v18, v120, v17
	v_fmac_f32_e32 v34, v120, v33
	v_fmac_f32_e32 v50, v122, v49
	v_fmac_f32_e32 v66, v122, v65
	v_fmac_f32_e32 v18, v124, v33
	v_fmac_f32_e32 v34, v121, v17
	v_fmac_f32_e32 v50, v125, v65
	v_fmac_f32_e32 v66, v123, v49
	v_cvt_pk_bf16_f32 v170, v18, v34
	v_cvt_pk_bf16_f32 v171, v50, v66
	ds_write2_b32 v14, v170, v171 offset0:136 offset1:168
	v_fmac_f32_e32 v19, v120, v18
	v_fmac_f32_e32 v35, v120, v34
	v_fmac_f32_e32 v51, v122, v50
	v_fmac_f32_e32 v67, v122, v66
	v_fmac_f32_e32 v19, v124, v34
	v_fmac_f32_e32 v35, v121, v18
	v_fmac_f32_e32 v51, v125, v66
	v_fmac_f32_e32 v67, v123, v50
	v_cvt_pk_bf16_f32 v170, v19, v35
	v_cvt_pk_bf16_f32 v171, v51, v67
	ds_write2_b32 v14, v170, v171 offset0:204 offset1:236
	v_fmac_f32_e32 v20, v120, v19
	v_fmac_f32_e32 v36, v120, v35
	v_fmac_f32_e32 v52, v122, v51
	v_fmac_f32_e32 v68, v122, v67
	v_fmac_f32_e32 v20, v124, v35
	v_fmac_f32_e32 v36, v121, v19
	v_fmac_f32_e32 v52, v125, v67
	v_fmac_f32_e32 v68, v123, v51
	v_cvt_pk_bf16_f32 v170, v20, v36
	v_cvt_pk_bf16_f32 v171, v52, v68
	ds_write2_b32 v15, v170, v171 offset1:32
	v_fmac_f32_e32 v21, v120, v20
	v_fmac_f32_e32 v37, v120, v36
	v_fmac_f32_e32 v53, v122, v52
	v_fmac_f32_e32 v69, v122, v68
	v_fmac_f32_e32 v21, v124, v36
	v_fmac_f32_e32 v37, v121, v20
	v_fmac_f32_e32 v53, v125, v68
	v_fmac_f32_e32 v69, v123, v52
	v_cvt_pk_bf16_f32 v170, v21, v37
	v_cvt_pk_bf16_f32 v171, v53, v69
	ds_write2_b32 v15, v170, v171 offset0:68 offset1:100
	v_fmac_f32_e32 v22, v120, v21
	v_fmac_f32_e32 v38, v120, v37
	v_fmac_f32_e32 v54, v122, v53
	v_fmac_f32_e32 v70, v122, v69
	v_fmac_f32_e32 v22, v124, v37
	v_fmac_f32_e32 v38, v121, v21
	v_fmac_f32_e32 v54, v125, v69
	v_fmac_f32_e32 v70, v123, v53
	v_cvt_pk_bf16_f32 v170, v22, v38
	v_cvt_pk_bf16_f32 v171, v54, v70
	ds_write2_b32 v15, v170, v171 offset0:136 offset1:168
	v_fmac_f32_e32 v23, v120, v22
	v_fmac_f32_e32 v39, v120, v38
	v_fmac_f32_e32 v55, v122, v54
	v_fmac_f32_e32 v71, v122, v70
	v_fmac_f32_e32 v23, v124, v38
	v_fmac_f32_e32 v39, v121, v22
	v_fmac_f32_e32 v55, v125, v70
	v_fmac_f32_e32 v71, v123, v54
	v_cvt_pk_bf16_f32 v170, v23, v39
	v_cvt_pk_bf16_f32 v171, v55, v71
	ds_write2_b32 v15, v170, v171 offset0:204 offset1:236
	v_fmac_f32_e32 v24, v120, v23
	v_fmac_f32_e32 v40, v120, v39
	v_fmac_f32_e32 v56, v122, v55
	v_fmac_f32_e32 v72, v122, v71
	v_fmac_f32_e32 v24, v124, v39
	v_fmac_f32_e32 v40, v121, v23
	v_fmac_f32_e32 v56, v125, v71
	v_fmac_f32_e32 v72, v123, v55
	v_cvt_pk_bf16_f32 v170, v24, v40
	v_cvt_pk_bf16_f32 v171, v56, v72
	ds_write2_b32 v184, v170, v171 offset1:32
	v_fmac_f32_e32 v25, v120, v24
	v_fmac_f32_e32 v41, v120, v40
	v_fmac_f32_e32 v57, v122, v56
	v_fmac_f32_e32 v73, v122, v72
	v_fmac_f32_e32 v25, v124, v40
	v_fmac_f32_e32 v41, v121, v24
	v_fmac_f32_e32 v57, v125, v72
	v_fmac_f32_e32 v73, v123, v56
	v_cvt_pk_bf16_f32 v170, v25, v41
	v_cvt_pk_bf16_f32 v171, v57, v73
	ds_write2_b32 v184, v170, v171 offset0:68 offset1:100
	v_fmac_f32_e32 v26, v120, v25
	v_fmac_f32_e32 v42, v120, v41
	v_fmac_f32_e32 v58, v122, v57
	v_fmac_f32_e32 v74, v122, v73
	v_fmac_f32_e32 v26, v124, v41
	v_fmac_f32_e32 v42, v121, v25
	v_fmac_f32_e32 v58, v125, v73
	v_fmac_f32_e32 v74, v123, v57
	v_cvt_pk_bf16_f32 v170, v26, v42
	v_cvt_pk_bf16_f32 v171, v58, v74
	ds_write2_b32 v184, v170, v171 offset0:136 offset1:168
	v_fmac_f32_e32 v27, v120, v26
	v_fmac_f32_e32 v43, v120, v42
	v_fmac_f32_e32 v59, v122, v58
	v_fmac_f32_e32 v75, v122, v74
	v_fmac_f32_e32 v27, v124, v42
	v_fmac_f32_e32 v43, v121, v26
	v_fmac_f32_e32 v59, v125, v74
	v_fmac_f32_e32 v75, v123, v58
	v_cvt_pk_bf16_f32 v170, v27, v43
	v_cvt_pk_bf16_f32 v171, v59, v75
	ds_write2_b32 v184, v170, v171 offset0:204 offset1:236
	v_fmac_f32_e32 v28, v120, v27
	v_fmac_f32_e32 v44, v120, v43
	v_fmac_f32_e32 v60, v122, v59
	v_fmac_f32_e32 v76, v122, v75
	v_fmac_f32_e32 v28, v124, v43
	v_fmac_f32_e32 v44, v121, v27
	v_fmac_f32_e32 v60, v125, v75
	v_fmac_f32_e32 v76, v123, v59
	v_cvt_pk_bf16_f32 v170, v28, v44
	v_cvt_pk_bf16_f32 v171, v60, v76
	ds_write2_b32 v185, v170, v171 offset1:32
	v_fmac_f32_e32 v29, v120, v28
	v_fmac_f32_e32 v45, v120, v44
	v_fmac_f32_e32 v61, v122, v60
	v_fmac_f32_e32 v77, v122, v76
	v_fmac_f32_e32 v29, v124, v44
	v_fmac_f32_e32 v45, v121, v28
	v_fmac_f32_e32 v61, v125, v76
	v_fmac_f32_e32 v77, v123, v60
	v_cvt_pk_bf16_f32 v170, v29, v45
	v_cvt_pk_bf16_f32 v171, v61, v77
	ds_write2_b32 v185, v170, v171 offset0:68 offset1:100
	v_fmac_f32_e32 v30, v120, v29
	v_fmac_f32_e32 v46, v120, v45
	v_fmac_f32_e32 v62, v122, v61
	v_fmac_f32_e32 v78, v122, v77
	v_fmac_f32_e32 v30, v124, v45
	v_fmac_f32_e32 v46, v121, v29
	v_fmac_f32_e32 v62, v125, v77
	v_fmac_f32_e32 v78, v123, v61
	v_cvt_pk_bf16_f32 v170, v30, v46
	v_cvt_pk_bf16_f32 v171, v62, v78
	ds_write2_b32 v185, v170, v171 offset0:136 offset1:168
	v_fmac_f32_e32 v31, v120, v30
	v_fmac_f32_e32 v47, v120, v46
	v_fmac_f32_e32 v63, v122, v62
	v_fmac_f32_e32 v79, v122, v78
	v_fmac_f32_e32 v31, v124, v46
	v_fmac_f32_e32 v47, v121, v30
	v_fmac_f32_e32 v63, v125, v78
	v_fmac_f32_e32 v79, v123, v62
	v_cvt_pk_bf16_f32 v170, v31, v47
	v_cvt_pk_bf16_f32 v171, v63, v79
	ds_write2_b32 v185, v170, v171 offset0:204 offset1:236
	v_mov_b32_e32 v126, v31
	v_mov_b32_e32 v127, v47
	v_mov_b32_e32 v128, v63
	v_mov_b32_e32 v129, v79
	ds_read_b128 v[130:133], v187
	ds_read_b128 v[134:137], v187 offset:64
	ds_read_b128 v[138:141], v187 offset:128
	ds_read_b128 v[142:145], v187 offset:192
	ds_read_b128 v[146:149], v187 offset:4352
	ds_read_b128 v[150:153], v187 offset:4416
	ds_read_b128 v[154:157], v187 offset:4480
	ds_read_b128 v[158:161], v187 offset:4544
	s_waitcnt vmcnt(3)
	v_mfma_f32_32x32x16_bf16 v[16:31], v[84:87], v[88:91], 0
	v_mfma_f32_32x32x16_bf16 v[32:47], v[84:87], v[92:95], 0
	v_mfma_f32_32x32x16_bf16 v[48:63], v[84:87], v[96:99], 0
	v_mfma_f32_32x32x16_bf16 v[64:79], v[84:87], v[100:103], 0
	s_waitcnt lgkmcnt(0)
	v_mfma_f32_16x16x32_bf16 v[162:165], v[104:107], v[130:133], 0
	v_mfma_f32_16x16x32_bf16 v[166:169], v[104:107], v[146:149], 0
	v_mfma_f32_16x16x32_bf16 v[162:165], v[108:111], v[134:137], v[162:165]
	v_mfma_f32_16x16x32_bf16 v[166:169], v[108:111], v[150:153], v[166:169]
	v_mfma_f32_16x16x32_bf16 v[162:165], v[112:115], v[138:141], v[162:165]
	v_mfma_f32_16x16x32_bf16 v[166:169], v[112:115], v[154:157], v[166:169]
	v_mfma_f32_16x16x32_bf16 v[162:165], v[116:119], v[142:145], v[162:165]
	v_mfma_f32_16x16x32_bf16 v[166:169], v[116:119], v[158:161], v[166:169]
	s_nop 7
	global_store_dwordx4 v188, v[162:165], s[12:13]
	global_store_dwordx4 v189, v[166:169], s[12:13]
	s_add_u32 s12, s12, 65536
	s_addc_u32 s13, s13, 0
	global_load_dwordx4 v[84:87], v186, s[10:11]
	s_add_u32 s34, s34, 98304
	s_addc_u32 s35, s35, 0
	s_add_u32 s10, s10, 98304
	s_addc_u32 s11, s11, 0
	v_fmac_f32_e32 v16, v120, v126
	v_fmac_f32_e32 v32, v120, v127
	v_fmac_f32_e32 v48, v122, v128
	v_fmac_f32_e32 v64, v122, v129
	v_fmac_f32_e32 v16, v124, v127
	v_fmac_f32_e32 v32, v121, v126
	v_fmac_f32_e32 v48, v125, v129
	v_fmac_f32_e32 v64, v123, v128
	v_cvt_pk_bf16_f32 v170, v16, v32
	v_cvt_pk_bf16_f32 v171, v48, v64
	ds_write2_b32 v14, v170, v171 offset1:32
	v_fmac_f32_e32 v17, v120, v16
	v_fmac_f32_e32 v33, v120, v32
	v_fmac_f32_e32 v49, v122, v48
	v_fmac_f32_e32 v65, v122, v64
	v_fmac_f32_e32 v17, v124, v32
	v_fmac_f32_e32 v33, v121, v16
	v_fmac_f32_e32 v49, v125, v64
	v_fmac_f32_e32 v65, v123, v48
	v_cvt_pk_bf16_f32 v170, v17, v33
	v_cvt_pk_bf16_f32 v171, v49, v65
	ds_write2_b32 v14, v170, v171 offset0:68 offset1:100
	v_fmac_f32_e32 v18, v120, v17
	v_fmac_f32_e32 v34, v120, v33
	v_fmac_f32_e32 v50, v122, v49
	v_fmac_f32_e32 v66, v122, v65
	v_fmac_f32_e32 v18, v124, v33
	v_fmac_f32_e32 v34, v121, v17
	v_fmac_f32_e32 v50, v125, v65
	v_fmac_f32_e32 v66, v123, v49
	v_cvt_pk_bf16_f32 v170, v18, v34
	v_cvt_pk_bf16_f32 v171, v50, v66
	ds_write2_b32 v14, v170, v171 offset0:136 offset1:168
	v_fmac_f32_e32 v19, v120, v18
	v_fmac_f32_e32 v35, v120, v34
	v_fmac_f32_e32 v51, v122, v50
	v_fmac_f32_e32 v67, v122, v66
	v_fmac_f32_e32 v19, v124, v34
	v_fmac_f32_e32 v35, v121, v18
	v_fmac_f32_e32 v51, v125, v66
	v_fmac_f32_e32 v67, v123, v50
	v_cvt_pk_bf16_f32 v170, v19, v35
	v_cvt_pk_bf16_f32 v171, v51, v67
	ds_write2_b32 v14, v170, v171 offset0:204 offset1:236
	v_fmac_f32_e32 v20, v120, v19
	v_fmac_f32_e32 v36, v120, v35
	v_fmac_f32_e32 v52, v122, v51
	v_fmac_f32_e32 v68, v122, v67
	v_fmac_f32_e32 v20, v124, v35
	v_fmac_f32_e32 v36, v121, v19
	v_fmac_f32_e32 v52, v125, v67
	v_fmac_f32_e32 v68, v123, v51
	v_cvt_pk_bf16_f32 v170, v20, v36
	v_cvt_pk_bf16_f32 v171, v52, v68
	ds_write2_b32 v15, v170, v171 offset1:32
	v_fmac_f32_e32 v21, v120, v20
	v_fmac_f32_e32 v37, v120, v36
	v_fmac_f32_e32 v53, v122, v52
	v_fmac_f32_e32 v69, v122, v68
	v_fmac_f32_e32 v21, v124, v36
	v_fmac_f32_e32 v37, v121, v20
	v_fmac_f32_e32 v53, v125, v68
	v_fmac_f32_e32 v69, v123, v52
	v_cvt_pk_bf16_f32 v170, v21, v37
	v_cvt_pk_bf16_f32 v171, v53, v69
	ds_write2_b32 v15, v170, v171 offset0:68 offset1:100
	v_fmac_f32_e32 v22, v120, v21
	v_fmac_f32_e32 v38, v120, v37
	v_fmac_f32_e32 v54, v122, v53
	v_fmac_f32_e32 v70, v122, v69
	v_fmac_f32_e32 v22, v124, v37
	v_fmac_f32_e32 v38, v121, v21
	v_fmac_f32_e32 v54, v125, v69
	v_fmac_f32_e32 v70, v123, v53
	v_cvt_pk_bf16_f32 v170, v22, v38
	v_cvt_pk_bf16_f32 v171, v54, v70
	ds_write2_b32 v15, v170, v171 offset0:136 offset1:168
	v_fmac_f32_e32 v23, v120, v22
	v_fmac_f32_e32 v39, v120, v38
	v_fmac_f32_e32 v55, v122, v54
	v_fmac_f32_e32 v71, v122, v70
	v_fmac_f32_e32 v23, v124, v38
	v_fmac_f32_e32 v39, v121, v22
	v_fmac_f32_e32 v55, v125, v70
	v_fmac_f32_e32 v71, v123, v54
	v_cvt_pk_bf16_f32 v170, v23, v39
	v_cvt_pk_bf16_f32 v171, v55, v71
	ds_write2_b32 v15, v170, v171 offset0:204 offset1:236
	v_fmac_f32_e32 v24, v120, v23
	v_fmac_f32_e32 v40, v120, v39
	v_fmac_f32_e32 v56, v122, v55
	v_fmac_f32_e32 v72, v122, v71
	v_fmac_f32_e32 v24, v124, v39
	v_fmac_f32_e32 v40, v121, v23
	v_fmac_f32_e32 v56, v125, v71
	v_fmac_f32_e32 v72, v123, v55
	v_cvt_pk_bf16_f32 v170, v24, v40
	v_cvt_pk_bf16_f32 v171, v56, v72
	ds_write2_b32 v184, v170, v171 offset1:32
	v_fmac_f32_e32 v25, v120, v24
	v_fmac_f32_e32 v41, v120, v40
	v_fmac_f32_e32 v57, v122, v56
	v_fmac_f32_e32 v73, v122, v72
	v_fmac_f32_e32 v25, v124, v40
	v_fmac_f32_e32 v41, v121, v24
	v_fmac_f32_e32 v57, v125, v72
	v_fmac_f32_e32 v73, v123, v56
	v_cvt_pk_bf16_f32 v170, v25, v41
	v_cvt_pk_bf16_f32 v171, v57, v73
	ds_write2_b32 v184, v170, v171 offset0:68 offset1:100
	v_fmac_f32_e32 v26, v120, v25
	v_fmac_f32_e32 v42, v120, v41
	v_fmac_f32_e32 v58, v122, v57
	v_fmac_f32_e32 v74, v122, v73
	v_fmac_f32_e32 v26, v124, v41
	v_fmac_f32_e32 v42, v121, v25
	v_fmac_f32_e32 v58, v125, v73
	v_fmac_f32_e32 v74, v123, v57
	v_cvt_pk_bf16_f32 v170, v26, v42
	v_cvt_pk_bf16_f32 v171, v58, v74
	ds_write2_b32 v184, v170, v171 offset0:136 offset1:168
	v_fmac_f32_e32 v27, v120, v26
	v_fmac_f32_e32 v43, v120, v42
	v_fmac_f32_e32 v59, v122, v58
	v_fmac_f32_e32 v75, v122, v74
	v_fmac_f32_e32 v27, v124, v42
	v_fmac_f32_e32 v43, v121, v26
	v_fmac_f32_e32 v59, v125, v74
	v_fmac_f32_e32 v75, v123, v58
	v_cvt_pk_bf16_f32 v170, v27, v43
	v_cvt_pk_bf16_f32 v171, v59, v75
	ds_write2_b32 v184, v170, v171 offset0:204 offset1:236
	v_fmac_f32_e32 v28, v120, v27
	v_fmac_f32_e32 v44, v120, v43
	v_fmac_f32_e32 v60, v122, v59
	v_fmac_f32_e32 v76, v122, v75
	v_fmac_f32_e32 v28, v124, v43
	v_fmac_f32_e32 v44, v121, v27
	v_fmac_f32_e32 v60, v125, v75
	v_fmac_f32_e32 v76, v123, v59
	v_cvt_pk_bf16_f32 v170, v28, v44
	v_cvt_pk_bf16_f32 v171, v60, v76
	ds_write2_b32 v185, v170, v171 offset1:32
	v_fmac_f32_e32 v29, v120, v28
	v_fmac_f32_e32 v45, v120, v44
	v_fmac_f32_e32 v61, v122, v60
	v_fmac_f32_e32 v77, v122, v76
	v_fmac_f32_e32 v29, v124, v44
	v_fmac_f32_e32 v45, v121, v28
	v_fmac_f32_e32 v61, v125, v76
	v_fmac_f32_e32 v77, v123, v60
	v_cvt_pk_bf16_f32 v170, v29, v45
	v_cvt_pk_bf16_f32 v171, v61, v77
	ds_write2_b32 v185, v170, v171 offset0:68 offset1:100
	v_fmac_f32_e32 v30, v120, v29
	v_fmac_f32_e32 v46, v120, v45
	v_fmac_f32_e32 v62, v122, v61
	v_fmac_f32_e32 v78, v122, v77
	v_fmac_f32_e32 v30, v124, v45
	v_fmac_f32_e32 v46, v121, v29
	v_fmac_f32_e32 v62, v125, v77
	v_fmac_f32_e32 v78, v123, v61
	v_cvt_pk_bf16_f32 v170, v30, v46
	v_cvt_pk_bf16_f32 v171, v62, v78
	ds_write2_b32 v185, v170, v171 offset0:136 offset1:168
	v_fmac_f32_e32 v31, v120, v30
	v_fmac_f32_e32 v47, v120, v46
	v_fmac_f32_e32 v63, v122, v62
	v_fmac_f32_e32 v79, v122, v78
	v_fmac_f32_e32 v31, v124, v46
	v_fmac_f32_e32 v47, v121, v30
	v_fmac_f32_e32 v63, v125, v78
	v_fmac_f32_e32 v79, v123, v62
	v_cvt_pk_bf16_f32 v170, v31, v47
	v_cvt_pk_bf16_f32 v171, v63, v79
	ds_write2_b32 v185, v170, v171 offset0:204 offset1:236
	v_mov_b32_e32 v126, v31
	v_mov_b32_e32 v127, v47
	v_mov_b32_e32 v128, v63
	v_mov_b32_e32 v129, v79
	s_add_u32 s14, s14, 2
	s_cmp_lt_u32 s14, 64
	s_cbranch_scc1 .Lssm_tile_d0m0
	ds_read_b128 v[130:133], v187
	ds_read_b128 v[134:137], v187 offset:64
	ds_read_b128 v[138:141], v187 offset:128
	ds_read_b128 v[142:145], v187 offset:192
	ds_read_b128 v[146:149], v187 offset:4352
	ds_read_b128 v[150:153], v187 offset:4416
	ds_read_b128 v[154:157], v187 offset:4480
	ds_read_b128 v[158:161], v187 offset:4544
	s_waitcnt vmcnt(0) lgkmcnt(0)
	v_mfma_f32_16x16x32_bf16 v[162:165], v[104:107], v[130:133], 0
	v_mfma_f32_16x16x32_bf16 v[166:169], v[104:107], v[146:149], 0
	v_mfma_f32_16x16x32_bf16 v[162:165], v[108:111], v[134:137], v[162:165]
	v_mfma_f32_16x16x32_bf16 v[166:169], v[108:111], v[150:153], v[166:169]
	v_mfma_f32_16x16x32_bf16 v[162:165], v[112:115], v[138:141], v[162:165]
	v_mfma_f32_16x16x32_bf16 v[166:169], v[112:115], v[154:157], v[166:169]
	v_mfma_f32_16x16x32_bf16 v[162:165], v[116:119], v[142:145], v[162:165]
	v_mfma_f32_16x16x32_bf16 v[166:169], v[116:119], v[158:161], v[166:169]
	s_nop 7
	global_store_dwordx4 v188, v[162:165], s[12:13]
	global_store_dwordx4 v189, v[166:169], s[12:13]
	s_waitcnt vmcnt(0) lgkmcnt(0)
	s_branch .Lssm_lat_join
.Lssm_lat_bwd:
	v_and_b32_e32 v6, 31, v191
	v_lshrrev_b32_e32 v7, 5, v191
	v_and_b32_e32 v8, 15, v191
	v_lshrrev_b32_e32 v9, 4, v191
	v_lshrrev_b32_e32 v10, 3, v6
	v_lshlrev_b32_e32 v10, 10, v10
	v_and_b32_e32 v11, 7, v6
	v_lshl_add_u32 v10, v11, 5, v10
	v_lshl_add_u32 v10, v7, 8, v10
	s_add_u32 s28, s24, 64
	s_lshl_b32 s29, s28, 13
	s_add_u32 s29, s29, 0x200000
	s_add_u32 s10, s62, s29
	s_addc_u32 s11, s63, 0
	s_add_u32 s12, s10, 0x1000
	s_addc_u32 s13, s11, 0
	global_load_dwordx4 v[88:91], v10, s[10:11]
	global_load_dwordx4 v[92:95], v10, s[10:11] offset:16
	global_load_dwordx4 v[96:99], v10, s[12:13]
	global_load_dwordx4 v[100:103], v10, s[12:13] offset:16
	s_lshl_b32 s29, s28, 12
	s_add_u32 s29, s29, 0x300000
	s_add_u32 s16, s62, s29
	s_addc_u32 s17, s63, 0
	v_lshlrev_b32_e32 v10, 4, v191
	global_load_dwordx4 v[104:107], v10, s[16:17]
	global_load_dwordx4 v[108:111], v10, s[16:17] offset:1024
	global_load_dwordx4 v[112:115], v10, s[16:17] offset:2048
	global_load_dwordx4 v[116:119], v10, s[16:17] offset:3072
	s_lshl_b32 s29, s28, 9
	s_add_u32 s29, s29, 0x100000
	s_add_u32 s18, s62, s29
	s_addc_u32 s19, s63, 0
	v_lshlrev_b32_e32 v10, 3, v6
	global_load_dwordx2 v[120:121], v10, s[18:19]
	global_load_dwordx2 v[122:123], v10, s[18:19] offset:256
	s_lshl_b32 s30, s23, 1
	s_add_u32 s30, s30, 1
	s_lshl_b32 s30, s30, 15
	s_lshl_b32 s31, s24, 8
	s_add_u32 s30, s30, s31
	v_lshlrev_b32_e32 v10, 16, v7
	v_lshl_add_u32 v10, v6, 2, v10
	v_mov_b32_e32 v196, v10
	v_readlane_b32 s34, v254, 10
	v_readlane_b32 s35, v254, 11
	s_nop 3
	s_add_u32 s34, s34, s30
	s_addc_u32 s35, s35, 0
	s_add_u32 s38, s34, 0x4000
	s_addc_u32 s39, s35, 0
	global_load_dword v126, v10, s[34:35]
	global_load_dword v128, v10, s[34:35] offset:128
	global_load_dword v127, v10, s[38:39]
	global_load_dword v129, v10, s[38:39] offset:128
	s_mul_i32 s31, s25, 0x1800
	s_lshl_b32 s29, s24, 5
	s_add_u32 s31, s31, s29
	s_add_u32 s31, s31, 0x8801000
	s_add_u32 s4, s62, s31
	s_addc_u32 s5, s63, 0
	v_lshrrev_b32_e32 v10, 3, v6
	v_and_b32_e32 v11, 3, v6
	v_lshl_add_u32 v10, v10, 2, v11
	v_mul_u32_u24_e32 v10, 0x1800, v10
	v_lshl_add_u32 v10, v7, 4, v10
	v_bfe_u32 v11, v6, 2, 1
	v_mul_u32_u24_e32 v11, 6291456, v11
	v_add_u32_e32 v186, v10, v11
	v_mul_u32_u24_e32 v10, 0x1100, v7
	v_lshl_add_u32 v10, v6, 2, v10
	v_add_u32_e32 v14, s20, v10
	v_add_u32_e32 v15, 1088, v14
	v_add_u32_e32 v184, 2176, v14
	v_add_u32_e32 v185, 3264, v14
	v_mul_u32_u24_e32 v10, 0x110, v8
	v_lshl_add_u32 v10, v9, 4, v10
	v_add_u32_e32 v187, s20, v10
	v_lshlrev_b32_e32 v10, 12, v8
	v_lshl_add_u32 v188, v9, 4, v10
	v_add_u32_e32 v189, 0x400000, v188
	s_lshl_b32 s31, s25, 12
	s_lshl_b32 s29, s24, 6
	s_add_u32 s31, s31, s29
	s_add_u32 s31, s31, 0x4000000
	s_add_u32 s6, s60, s31
	s_addc_u32 s7, s61, 0
	s_add_u32 s34, s4, 6193152
	s_addc_u32 s35, s5, 0
	global_load_dwordx4 v[80:83], v186, s[34:35]
	s_mov_b64 s[10:11], s[34:35]
	s_sub_u32 s10, s10, 98304
	s_subb_u32 s11, s11, 0
	global_load_dwordx4 v[84:87], v186, s[10:11]
	s_mov_b64 s[34:35], s[10:11]
	s_sub_u32 s10, s10, 98304
	s_subb_u32 s11, s11, 0
	s_add_u32 s12, s6, 4128768
	s_addc_u32 s13, s7, 0
	s_mov_b32 s14, 0
	s_waitcnt vmcnt(0)
	v_xor_b32_e32 v124, 0x80000000, v121
	v_xor_b32_e32 v125, 0x80000000, v123

.Lssm_sk1_d1m0:
	s_waitcnt vmcnt(3)
	v_mfma_f32_32x32x16_bf16 v[16:31], v[80:83], v[88:91], 0
	v_mfma_f32_32x32x16_bf16 v[32:47], v[80:83], v[92:95], 0
	v_mfma_f32_32x32x16_bf16 v[48:63], v[80:83], v[96:99], 0
	v_mfma_f32_32x32x16_bf16 v[64:79], v[80:83], v[100:103], 0
	s_cmp_eq_u32 s14, 0
	s_cbranch_scc1 .Lssm_sk3_d1m0
	s_waitcnt lgkmcnt(0)
	v_mfma_f32_16x16x32_bf16 v[162:165], v[104:107], v[130:133], 0
	v_mfma_f32_16x16x32_bf16 v[166:169], v[104:107], v[146:149], 0
	v_mfma_f32_16x16x32_bf16 v[162:165], v[108:111], v[134:137], v[162:165]
	v_mfma_f32_16x16x32_bf16 v[166:169], v[108:111], v[150:153], v[166:169]
	v_mfma_f32_16x16x32_bf16 v[162:165], v[112:115], v[138:141], v[162:165]
	v_mfma_f32_16x16x32_bf16 v[166:169], v[112:115], v[154:157], v[166:169]
	v_mfma_f32_16x16x32_bf16 v[162:165], v[116:119], v[142:145], v[162:165]
	v_mfma_f32_16x16x32_bf16 v[166:169], v[116:119], v[158:161], v[166:169]
	s_nop 7
	global_store_dwordx4 v188, v[162:165], s[12:13]
	global_store_dwordx4 v189, v[166:169], s[12:13]
	s_sub_u32 s12, s12, 65536
	s_subb_u32 s13, s13, 0
.Lssm_sk3_d1m0:
	s_nop 9
	global_load_dwordx4 v[80:83], v186, s[10:11]
	s_sub_u32 s34, s34, 98304
	s_subb_u32 s35, s35, 0
	s_sub_u32 s10, s10, 98304
	s_subb_u32 s11, s11, 0
	v_fmac_f32_e32 v31, v120, v126
	v_fmac_f32_e32 v47, v120, v127
	v_fmac_f32_e32 v63, v122, v128
	v_fmac_f32_e32 v79, v122, v129
	v_fmac_f32_e32 v31, v124, v127
	v_fmac_f32_e32 v47, v121, v126
	v_fmac_f32_e32 v63, v125, v129
	v_fmac_f32_e32 v79, v123, v128
	v_cvt_pk_bf16_f32 v170, v31, v47
	v_cvt_pk_bf16_f32 v171, v63, v79
	ds_write2_b32 v185, v170, v171 offset0:204 offset1:236
	v_fmac_f32_e32 v30, v120, v31
	v_fmac_f32_e32 v46, v120, v47
	v_fmac_f32_e32 v62, v122, v63
	v_fmac_f32_e32 v78, v122, v79
	v_fmac_f32_e32 v30, v124, v47
	v_fmac_f32_e32 v46, v121, v31
	v_fmac_f32_e32 v62, v125, v79
	v_fmac_f32_e32 v78, v123, v63
	v_cvt_pk_bf16_f32 v170, v30, v46
	v_cvt_pk_bf16_f32 v171, v62, v78
	ds_write2_b32 v185, v170, v171 offset0:136 offset1:168
	v_fmac_f32_e32 v29, v120, v30
	v_fmac_f32_e32 v45, v120, v46
	v_fmac_f32_e32 v61, v122, v62
	v_fmac_f32_e32 v77, v122, v78
	v_fmac_f32_e32 v29, v124, v46
	v_fmac_f32_e32 v45, v121, v30
	v_fmac_f32_e32 v61, v125, v78
	v_fmac_f32_e32 v77, v123, v62
	v_cvt_pk_bf16_f32 v170, v29, v45
	v_cvt_pk_bf16_f32 v171, v61, v77
	ds_write2_b32 v185, v170, v171 offset0:68 offset1:100
	v_fmac_f32_e32 v28, v120, v29
	v_fmac_f32_e32 v44, v120, v45
	v_fmac_f32_e32 v60, v122, v61
	v_fmac_f32_e32 v76, v122, v77
	v_fmac_f32_e32 v28, v124, v45
	v_fmac_f32_e32 v44, v121, v29
	v_fmac_f32_e32 v60, v125, v77
	v_fmac_f32_e32 v76, v123, v61
	v_cvt_pk_bf16_f32 v170, v28, v44
	v_cvt_pk_bf16_f32 v171, v60, v76
	ds_write2_b32 v185, v170, v171 offset1:32
	v_fmac_f32_e32 v27, v120, v28
	v_fmac_f32_e32 v43, v120, v44
	v_fmac_f32_e32 v59, v122, v60
	v_fmac_f32_e32 v75, v122, v76
	v_fmac_f32_e32 v27, v124, v44
	v_fmac_f32_e32 v43, v121, v28
	v_fmac_f32_e32 v59, v125, v76
	v_fmac_f32_e32 v75, v123, v60
	v_cvt_pk_bf16_f32 v170, v27, v43
	v_cvt_pk_bf16_f32 v171, v59, v75
	ds_write2_b32 v184, v170, v171 offset0:204 offset1:236
	v_fmac_f32_e32 v26, v120, v27
	v_fmac_f32_e32 v42, v120, v43
	v_fmac_f32_e32 v58, v122, v59
	v_fmac_f32_e32 v74, v122, v75
	v_fmac_f32_e32 v26, v124, v43
	v_fmac_f32_e32 v42, v121, v27
	v_fmac_f32_e32 v58, v125, v75
	v_fmac_f32_e32 v74, v123, v59
	v_cvt_pk_bf16_f32 v170, v26, v42
	v_cvt_pk_bf16_f32 v171, v58, v74
	ds_write2_b32 v184, v170, v171 offset0:136 offset1:168
	v_fmac_f32_e32 v25, v120, v26
	v_fmac_f32_e32 v41, v120, v42
	v_fmac_f32_e32 v57, v122, v58
	v_fmac_f32_e32 v73, v122, v74
	v_fmac_f32_e32 v25, v124, v42
	v_fmac_f32_e32 v41, v121, v26
	v_fmac_f32_e32 v57, v125, v74
	v_fmac_f32_e32 v73, v123, v58
	v_cvt_pk_bf16_f32 v170, v25, v41
	v_cvt_pk_bf16_f32 v171, v57, v73
	ds_write2_b32 v184, v170, v171 offset0:68 offset1:100
	v_fmac_f32_e32 v24, v120, v25
	v_fmac_f32_e32 v40, v120, v41
	v_fmac_f32_e32 v56, v122, v57
	v_fmac_f32_e32 v72, v122, v73
	v_fmac_f32_e32 v24, v124, v41
	v_fmac_f32_e32 v40, v121, v25
	v_fmac_f32_e32 v56, v125, v73
	v_fmac_f32_e32 v72, v123, v57
	v_cvt_pk_bf16_f32 v170, v24, v40
	v_cvt_pk_bf16_f32 v171, v56, v72
	ds_write2_b32 v184, v170, v171 offset1:32
	v_fmac_f32_e32 v23, v120, v24
	v_fmac_f32_e32 v39, v120, v40
	v_fmac_f32_e32 v55, v122, v56
	v_fmac_f32_e32 v71, v122, v72
	v_fmac_f32_e32 v23, v124, v40
	v_fmac_f32_e32 v39, v121, v24
	v_fmac_f32_e32 v55, v125, v72
	v_fmac_f32_e32 v71, v123, v56
	v_cvt_pk_bf16_f32 v170, v23, v39
	v_cvt_pk_bf16_f32 v171, v55, v71
	ds_write2_b32 v15, v170, v171 offset0:204 offset1:236
	v_fmac_f32_e32 v22, v120, v23
	v_fmac_f32_e32 v38, v120, v39
	v_fmac_f32_e32 v54, v122, v55
	v_fmac_f32_e32 v70, v122, v71
	v_fmac_f32_e32 v22, v124, v39
	v_fmac_f32_e32 v38, v121, v23
	v_fmac_f32_e32 v54, v125, v71
	v_fmac_f32_e32 v70, v123, v55
	v_cvt_pk_bf16_f32 v170, v22, v38
	v_cvt_pk_bf16_f32 v171, v54, v70
	ds_write2_b32 v15, v170, v171 offset0:136 offset1:168
	v_fmac_f32_e32 v21, v120, v22
	v_fmac_f32_e32 v37, v120, v38
	v_fmac_f32_e32 v53, v122, v54
	v_fmac_f32_e32 v69, v122, v70
	v_fmac_f32_e32 v21, v124, v38
	v_fmac_f32_e32 v37, v121, v22
	v_fmac_f32_e32 v53, v125, v70
	v_fmac_f32_e32 v69, v123, v54
	v_cvt_pk_bf16_f32 v170, v21, v37
	v_cvt_pk_bf16_f32 v171, v53, v69
	ds_write2_b32 v15, v170, v171 offset0:68 offset1:100
	v_fmac_f32_e32 v20, v120, v21
	v_fmac_f32_e32 v36, v120, v37
	v_fmac_f32_e32 v52, v122, v53
	v_fmac_f32_e32 v68, v122, v69
	v_fmac_f32_e32 v20, v124, v37
	v_fmac_f32_e32 v36, v121, v21
	v_fmac_f32_e32 v52, v125, v69
	v_fmac_f32_e32 v68, v123, v53
	v_cvt_pk_bf16_f32 v170, v20, v36
	v_cvt_pk_bf16_f32 v171, v52, v68
	ds_write2_b32 v15, v170, v171 offset1:32
	v_fmac_f32_e32 v19, v120, v20
	v_fmac_f32_e32 v35, v120, v36
	v_fmac_f32_e32 v51, v122, v52
	v_fmac_f32_e32 v67, v122, v68
	v_fmac_f32_e32 v19, v124, v36
	v_fmac_f32_e32 v35, v121, v20
	v_fmac_f32_e32 v51, v125, v68
	v_fmac_f32_e32 v67, v123, v52
	v_cvt_pk_bf16_f32 v170, v19, v35
	v_cvt_pk_bf16_f32 v171, v51, v67
	ds_write2_b32 v14, v170, v171 offset0:204 offset1:236
	v_fmac_f32_e32 v18, v120, v19
	v_fmac_f32_e32 v34, v120, v35
	v_fmac_f32_e32 v50, v122, v51
	v_fmac_f32_e32 v66, v122, v67
	v_fmac_f32_e32 v18, v124, v35
	v_fmac_f32_e32 v34, v121, v19
	v_fmac_f32_e32 v50, v125, v67
	v_fmac_f32_e32 v66, v123, v51
	v_cvt_pk_bf16_f32 v170, v18, v34
	v_cvt_pk_bf16_f32 v171, v50, v66
	ds_write2_b32 v14, v170, v171 offset0:136 offset1:168
	v_fmac_f32_e32 v17, v120, v18
	v_fmac_f32_e32 v33, v120, v34
	v_fmac_f32_e32 v49, v122, v50
	v_fmac_f32_e32 v65, v122, v66
	v_fmac_f32_e32 v17, v124, v34
	v_fmac_f32_e32 v33, v121, v18
	v_fmac_f32_e32 v49, v125, v66
	v_fmac_f32_e32 v65, v123, v50
	v_cvt_pk_bf16_f32 v170, v17, v33
	v_cvt_pk_bf16_f32 v171, v49, v65
	ds_write2_b32 v14, v170, v171 offset0:68 offset1:100
	v_fmac_f32_e32 v16, v120, v17
	v_fmac_f32_e32 v32, v120, v33
	v_fmac_f32_e32 v48, v122, v49
	v_fmac_f32_e32 v64, v122, v65
	v_fmac_f32_e32 v16, v124, v33
	v_fmac_f32_e32 v32, v121, v17
	v_fmac_f32_e32 v48, v125, v65
	v_fmac_f32_e32 v64, v123, v49
	v_cvt_pk_bf16_f32 v170, v16, v32
	v_cvt_pk_bf16_f32 v171, v48, v64
	ds_write2_b32 v14, v170, v171 offset1:32
	v_mov_b32_e32 v126, v16
	v_mov_b32_e32 v127, v32
	v_mov_b32_e32 v128, v48
	v_mov_b32_e32 v129, v64
	ds_read_b128 v[130:133], v187
	ds_read_b128 v[134:137], v187 offset:64
	ds_read_b128 v[138:141], v187 offset:128
	ds_read_b128 v[142:145], v187 offset:192
	ds_read_b128 v[146:149], v187 offset:4352
	ds_read_b128 v[150:153], v187 offset:4416
	ds_read_b128 v[154:157], v187 offset:4480
	ds_read_b128 v[158:161], v187 offset:4544
	s_waitcnt vmcnt(3)
	v_mfma_f32_32x32x16_bf16 v[16:31], v[84:87], v[88:91], 0
	v_mfma_f32_32x32x16_bf16 v[32:47], v[84:87], v[92:95], 0
	v_mfma_f32_32x32x16_bf16 v[48:63], v[84:87], v[96:99], 0
	v_mfma_f32_32x32x16_bf16 v[64:79], v[84:87], v[100:103], 0
	s_waitcnt lgkmcnt(0)
	v_mfma_f32_16x16x32_bf16 v[162:165], v[104:107], v[130:133], 0
	v_mfma_f32_16x16x32_bf16 v[166:169], v[104:107], v[146:149], 0
	v_mfma_f32_16x16x32_bf16 v[162:165], v[108:111], v[134:137], v[162:165]
	v_mfma_f32_16x16x32_bf16 v[166:169], v[108:111], v[150:153], v[166:169]
	v_mfma_f32_16x16x32_bf16 v[162:165], v[112:115], v[138:141], v[162:165]
	v_mfma_f32_16x16x32_bf16 v[166:169], v[112:115], v[154:157], v[166:169]
	v_mfma_f32_16x16x32_bf16 v[162:165], v[116:119], v[142:145], v[162:165]
	v_mfma_f32_16x16x32_bf16 v[166:169], v[116:119], v[158:161], v[166:169]
	s_nop 7
	global_store_dwordx4 v188, v[162:165], s[12:13]
	global_store_dwordx4 v189, v[166:169], s[12:13]
	s_sub_u32 s12, s12, 65536
	s_subb_u32 s13, s13, 0
	global_load_dwordx4 v[84:87], v186, s[10:11]
	s_sub_u32 s34, s34, 98304
	s_subb_u32 s35, s35, 0
	s_sub_u32 s10, s10, 98304
	s_subb_u32 s11, s11, 0
	v_fmac_f32_e32 v31, v120, v126
	v_fmac_f32_e32 v47, v120, v127
	v_fmac_f32_e32 v63, v122, v128
	v_fmac_f32_e32 v79, v122, v129
	v_fmac_f32_e32 v31, v124, v127
	v_fmac_f32_e32 v47, v121, v126
	v_fmac_f32_e32 v63, v125, v129
	v_fmac_f32_e32 v79, v123, v128
	v_cvt_pk_bf16_f32 v170, v31, v47
	v_cvt_pk_bf16_f32 v171, v63, v79
	ds_write2_b32 v185, v170, v171 offset0:204 offset1:236
	v_fmac_f32_e32 v30, v120, v31
	v_fmac_f32_e32 v46, v120, v47
	v_fmac_f32_e32 v62, v122, v63
	v_fmac_f32_e32 v78, v122, v79
	v_fmac_f32_e32 v30, v124, v47
	v_fmac_f32_e32 v46, v121, v31
	v_fmac_f32_e32 v62, v125, v79
	v_fmac_f32_e32 v78, v123, v63
	v_cvt_pk_bf16_f32 v170, v30, v46
	v_cvt_pk_bf16_f32 v171, v62, v78
	ds_write2_b32 v185, v170, v171 offset0:136 offset1:168
	v_fmac_f32_e32 v29, v120, v30
	v_fmac_f32_e32 v45, v120, v46
	v_fmac_f32_e32 v61, v122, v62
	v_fmac_f32_e32 v77, v122, v78
	v_fmac_f32_e32 v29, v124, v46
	v_fmac_f32_e32 v45, v121, v30
	v_fmac_f32_e32 v61, v125, v78
	v_fmac_f32_e32 v77, v123, v62
	v_cvt_pk_bf16_f32 v170, v29, v45
	v_cvt_pk_bf16_f32 v171, v61, v77
	ds_write2_b32 v185, v170, v171 offset0:68 offset1:100
	v_fmac_f32_e32 v28, v120, v29
	v_fmac_f32_e32 v44, v120, v45
	v_fmac_f32_e32 v60, v122, v61
	v_fmac_f32_e32 v76, v122, v77
	v_fmac_f32_e32 v28, v124, v45
	v_fmac_f32_e32 v44, v121, v29
	v_fmac_f32_e32 v60, v125, v77
	v_fmac_f32_e32 v76, v123, v61
	v_cvt_pk_bf16_f32 v170, v28, v44
	v_cvt_pk_bf16_f32 v171, v60, v76
	ds_write2_b32 v185, v170, v171 offset1:32
	v_fmac_f32_e32 v27, v120, v28
	v_fmac_f32_e32 v43, v120, v44
	v_fmac_f32_e32 v59, v122, v60
	v_fmac_f32_e32 v75, v122, v76
	v_fmac_f32_e32 v27, v124, v44
	v_fmac_f32_e32 v43, v121, v28
	v_fmac_f32_e32 v59, v125, v76
	v_fmac_f32_e32 v75, v123, v60
	v_cvt_pk_bf16_f32 v170, v27, v43
	v_cvt_pk_bf16_f32 v171, v59, v75
	ds_write2_b32 v184, v170, v171 offset0:204 offset1:236
	v_fmac_f32_e32 v26, v120, v27
	v_fmac_f32_e32 v42, v120, v43
	v_fmac_f32_e32 v58, v122, v59
	v_fmac_f32_e32 v74, v122, v75
	v_fmac_f32_e32 v26, v124, v43
	v_fmac_f32_e32 v42, v121, v27
	v_fmac_f32_e32 v58, v125, v75
	v_fmac_f32_e32 v74, v123, v59
	v_cvt_pk_bf16_f32 v170, v26, v42
	v_cvt_pk_bf16_f32 v171, v58, v74
	ds_write2_b32 v184, v170, v171 offset0:136 offset1:168
	v_fmac_f32_e32 v25, v120, v26
	v_fmac_f32_e32 v41, v120, v42
	v_fmac_f32_e32 v57, v122, v58
	v_fmac_f32_e32 v73, v122, v74
	v_fmac_f32_e32 v25, v124, v42
	v_fmac_f32_e32 v41, v121, v26
	v_fmac_f32_e32 v57, v125, v74
	v_fmac_f32_e32 v73, v123, v58
	v_cvt_pk_bf16_f32 v170, v25, v41
	v_cvt_pk_bf16_f32 v171, v57, v73
	ds_write2_b32 v184, v170, v171 offset0:68 offset1:100
	v_fmac_f32_e32 v24, v120, v25
	v_fmac_f32_e32 v40, v120, v41
	v_fmac_f32_e32 v56, v122, v57
	v_fmac_f32_e32 v72, v122, v73
	v_fmac_f32_e32 v24, v124, v41
	v_fmac_f32_e32 v40, v121, v25
	v_fmac_f32_e32 v56, v125, v73
	v_fmac_f32_e32 v72, v123, v57
	v_cvt_pk_bf16_f32 v170, v24, v40
	v_cvt_pk_bf16_f32 v171, v56, v72
	ds_write2_b32 v184, v170, v171 offset1:32
	v_fmac_f32_e32 v23, v120, v24
	v_fmac_f32_e32 v39, v120, v40
	v_fmac_f32_e32 v55, v122, v56
	v_fmac_f32_e32 v71, v122, v72
	v_fmac_f32_e32 v23, v124, v40
	v_fmac_f32_e32 v39, v121, v24
	v_fmac_f32_e32 v55, v125, v72
	v_fmac_f32_e32 v71, v123, v56
	v_cvt_pk_bf16_f32 v170, v23, v39
	v_cvt_pk_bf16_f32 v171, v55, v71
	ds_write2_b32 v15, v170, v171 offset0:204 offset1:236
	v_fmac_f32_e32 v22, v120, v23
	v_fmac_f32_e32 v38, v120, v39
	v_fmac_f32_e32 v54, v122, v55
	v_fmac_f32_e32 v70, v122, v71
	v_fmac_f32_e32 v22, v124, v39
	v_fmac_f32_e32 v38, v121, v23
	v_fmac_f32_e32 v54, v125, v71
	v_fmac_f32_e32 v70, v123, v55
	v_cvt_pk_bf16_f32 v170, v22, v38
	v_cvt_pk_bf16_f32 v171, v54, v70
	ds_write2_b32 v15, v170, v171 offset0:136 offset1:168
	v_fmac_f32_e32 v21, v120, v22
	v_fmac_f32_e32 v37, v120, v38
	v_fmac_f32_e32 v53, v122, v54
	v_fmac_f32_e32 v69, v122, v70
	v_fmac_f32_e32 v21, v124, v38
	v_fmac_f32_e32 v37, v121, v22
	v_fmac_f32_e32 v53, v125, v70
	v_fmac_f32_e32 v69, v123, v54
	v_cvt_pk_bf16_f32 v170, v21, v37
	v_cvt_pk_bf16_f32 v171, v53, v69
	ds_write2_b32 v15, v170, v171 offset0:68 offset1:100
	v_fmac_f32_e32 v20, v120, v21
	v_fmac_f32_e32 v36, v120, v37
	v_fmac_f32_e32 v52, v122, v53
	v_fmac_f32_e32 v68, v122, v69
	v_fmac_f32_e32 v20, v124, v37
	v_fmac_f32_e32 v36, v121, v21
	v_fmac_f32_e32 v52, v125, v69
	v_fmac_f32_e32 v68, v123, v53
	v_cvt_pk_bf16_f32 v170, v20, v36
	v_cvt_pk_bf16_f32 v171, v52, v68
	ds_write2_b32 v15, v170, v171 offset1:32
	v_fmac_f32_e32 v19, v120, v20
	v_fmac_f32_e32 v35, v120, v36
	v_fmac_f32_e32 v51, v122, v52
	v_fmac_f32_e32 v67, v122, v68
	v_fmac_f32_e32 v19, v124, v36
	v_fmac_f32_e32 v35, v121, v20
	v_fmac_f32_e32 v51, v125, v68
	v_fmac_f32_e32 v67, v123, v52
	v_cvt_pk_bf16_f32 v170, v19, v35
	v_cvt_pk_bf16_f32 v171, v51, v67
	ds_write2_b32 v14, v170, v171 offset0:204 offset1:236
	v_fmac_f32_e32 v18, v120, v19
	v_fmac_f32_e32 v34, v120, v35
	v_fmac_f32_e32 v50, v122, v51
	v_fmac_f32_e32 v66, v122, v67
	v_fmac_f32_e32 v18, v124, v35
	v_fmac_f32_e32 v34, v121, v19
	v_fmac_f32_e32 v50, v125, v67
	v_fmac_f32_e32 v66, v123, v51
	v_cvt_pk_bf16_f32 v170, v18, v34
	v_cvt_pk_bf16_f32 v171, v50, v66
	ds_write2_b32 v14, v170, v171 offset0:136 offset1:168
	v_fmac_f32_e32 v17, v120, v18
	v_fmac_f32_e32 v33, v120, v34
	v_fmac_f32_e32 v49, v122, v50
	v_fmac_f32_e32 v65, v122, v66
	v_fmac_f32_e32 v17, v124, v34
	v_fmac_f32_e32 v33, v121, v18
	v_fmac_f32_e32 v49, v125, v66
	v_fmac_f32_e32 v65, v123, v50
	v_cvt_pk_bf16_f32 v170, v17, v33
	v_cvt_pk_bf16_f32 v171, v49, v65
	ds_write2_b32 v14, v170, v171 offset0:68 offset1:100
	v_fmac_f32_e32 v16, v120, v17
	v_fmac_f32_e32 v32, v120, v33
	v_fmac_f32_e32 v48, v122, v49
	v_fmac_f32_e32 v64, v122, v65
	v_fmac_f32_e32 v16, v124, v33
	v_fmac_f32_e32 v32, v121, v17
	v_fmac_f32_e32 v48, v125, v65
	v_fmac_f32_e32 v64, v123, v49
	v_cvt_pk_bf16_f32 v170, v16, v32
	v_cvt_pk_bf16_f32 v171, v48, v64
	ds_write2_b32 v14, v170, v171 offset1:32
	v_mov_b32_e32 v126, v16
	v_mov_b32_e32 v127, v32
	v_mov_b32_e32 v128, v48
	v_mov_b32_e32 v129, v64
	s_add_u32 s14, s14, 2
	s_cmp_lt_u32 s14, 64
	s_cbranch_scc1 .Lssm_tile_d1m0
	ds_read_b128 v[130:133], v187
	ds_read_b128 v[134:137], v187 offset:64
	ds_read_b128 v[138:141], v187 offset:128
	ds_read_b128 v[142:145], v187 offset:192
	ds_read_b128 v[146:149], v187 offset:4352
	ds_read_b128 v[150:153], v187 offset:4416
	ds_read_b128 v[154:157], v187 offset:4480
	ds_read_b128 v[158:161], v187 offset:4544
	s_waitcnt vmcnt(0) lgkmcnt(0)
	v_mfma_f32_16x16x32_bf16 v[162:165], v[104:107], v[130:133], 0
	v_mfma_f32_16x16x32_bf16 v[166:169], v[104:107], v[146:149], 0
	v_mfma_f32_16x16x32_bf16 v[162:165], v[108:111], v[134:137], v[162:165]
	v_mfma_f32_16x16x32_bf16 v[166:169], v[108:111], v[150:153], v[166:169]
	v_mfma_f32_16x16x32_bf16 v[162:165], v[112:115], v[138:141], v[162:165]
	v_mfma_f32_16x16x32_bf16 v[166:169], v[112:115], v[154:157], v[166:169]
	v_mfma_f32_16x16x32_bf16 v[162:165], v[116:119], v[142:145], v[162:165]
	v_mfma_f32_16x16x32_bf16 v[166:169], v[116:119], v[158:161], v[166:169]
	s_nop 7
	global_store_dwordx4 v188, v[162:165], s[12:13]
	global_store_dwordx4 v189, v[166:169], s[12:13]
	s_waitcnt vmcnt(0) lgkmcnt(0)
.Lssm_lat_join:
	v_mov_b32_e32 v2, 0x21000
	v_mov_b32_e32 v3, 1
	v_cmp_eq_u32_e32 vcc, 0, v191
	s_and_saveexec_b64 s[0:1], vcc
	ds_add_u32 v2, v3
	s_mov_b64 exec, s[0:1]
	s_waitcnt lgkmcnt(0)
.Lssm_spin_pre:
	v_mov_b32_e32 v2, 0x21000
	s_mov_b32 s38, 0
.Lssm_spin:
	ds_read_b32 v3, v2
	s_waitcnt lgkmcnt(0)
	v_readfirstlane_b32 s39, v3
	s_nop 3
	s_cmp_ge_u32 s39, 2
	s_cbranch_scc1 .Lssm_spin_done
	s_sleep 8
	s_add_u32 s38, s38, 1
	s_cmp_lt_u32 s38, 0x100000
	s_cbranch_scc1 .Lssm_spin
.Lssm_spin_done:
	s_lshr_b32 s26, s89, 2
	s_lshl_b32 s26, s26, 10
	s_and_b32 s27, s89, 1
	s_lshl_b32 s27, s27, 9
	s_add_u32 s26, s26, s27
	s_add_u32 s26, s26, s25
	v_lshrrev_b32_e32 v6, 2, v191
	v_and_b32_e32 v7, 3, v191
	v_lshlrev_b32_e32 v8, 12, v6
	v_lshl_add_u32 v8, v7, 4, v8
	v_mul_u32_u24_e32 v9, 0x1800, v6
	v_lshl_add_u32 v9, v7, 3, v9
	v_lshlrev_b32_e32 v10, 11, v6
	v_lshl_add_u32 v10, v7, 3, v10
	v_lshlrev_b32_e32 v11, 4, v7
	s_lshl_b32 s31, s26, 12
	s_lshl_b32 s29, s24, 6
	s_add_u32 s31, s31, s29
	s_add_u32 s4, s60, s31
	s_addc_u32 s5, s61, 0
	s_add_u32 s6, s4, 0x4000000
	s_addc_u32 s7, s5, 0
	s_mul_i32 s31, s26, 0x1800
	s_lshl_b32 s29, s24, 5
	s_add_u32 s31, s31, s29
	s_add_u32 s31, s31, 0x8801000
	s_add_u32 s10, s62, s31
	s_addc_u32 s11, s63, 0
	s_lshl_b32 s31, s26, 11
	s_add_u32 s31, s31, s29
	s_add_u32 s31, s31, 0x14800000
	s_add_u32 s12, s62, s31
	s_addc_u32 s13, s63, 0
	v_readlane_b32 s16, v254, 28
	v_readlane_b32 s17, v254, 29
	s_nop 3
	s_lshl_b32 s31, s24, 6
	s_add_u32 s16, s16, s31
	s_addc_u32 s17, s17, 0
	s_nop 1
	global_load_dwordx4 v[176:179], v11, s[16:17]
	s_mov_b32 s14, 0
	v_mov_b32_e32 v1, 0x3dd2d3e8
.Lssm_comb:
	global_load_dwordx4 v[16:19], v8, s[4:5]
	global_load_dwordx4 v[48:51], v8, s[6:7]
	global_load_dwordx2 v[80:81], v9, s[10:11]
	s_add_u32 s4, s4, 65536
	s_addc_u32 s5, s5, 0
	s_add_u32 s6, s6, 65536
	s_addc_u32 s7, s7, 0
	s_add_u32 s10, s10, 98304
	s_addc_u32 s11, s11, 0
	global_load_dwordx4 v[20:23], v8, s[4:5]
	global_load_dwordx4 v[52:55], v8, s[6:7]
	global_load_dwordx2 v[82:83], v9, s[10:11]
	s_add_u32 s4, s4, 65536
	s_addc_u32 s5, s5, 0
	s_add_u32 s6, s6, 65536
	s_addc_u32 s7, s7, 0
	s_add_u32 s10, s10, 98304
	s_addc_u32 s11, s11, 0
	global_load_dwordx4 v[24:27], v8, s[4:5]
	global_load_dwordx4 v[56:59], v8, s[6:7]
	global_load_dwordx2 v[84:85], v9, s[10:11]
	s_add_u32 s4, s4, 65536
	s_addc_u32 s5, s5, 0
	s_add_u32 s6, s6, 65536
	s_addc_u32 s7, s7, 0
	s_add_u32 s10, s10, 98304
	s_addc_u32 s11, s11, 0
	global_load_dwordx4 v[28:31], v8, s[4:5]
	global_load_dwordx4 v[60:63], v8, s[6:7]
	global_load_dwordx2 v[86:87], v9, s[10:11]
	s_add_u32 s4, s4, 65536
	s_addc_u32 s5, s5, 0
	s_add_u32 s6, s6, 65536
	s_addc_u32 s7, s7, 0
	s_add_u32 s10, s10, 98304
	s_addc_u32 s11, s11, 0
	global_load_dwordx4 v[32:35], v8, s[4:5]
	global_load_dwordx4 v[64:67], v8, s[6:7]
	global_load_dwordx2 v[88:89], v9, s[10:11]
	s_add_u32 s4, s4, 65536
	s_addc_u32 s5, s5, 0
	s_add_u32 s6, s6, 65536
	s_addc_u32 s7, s7, 0
	s_add_u32 s10, s10, 98304
	s_addc_u32 s11, s11, 0
	global_load_dwordx4 v[36:39], v8, s[4:5]
	global_load_dwordx4 v[68:71], v8, s[6:7]
	global_load_dwordx2 v[90:91], v9, s[10:11]
	s_add_u32 s4, s4, 65536
	s_addc_u32 s5, s5, 0
	s_add_u32 s6, s6, 65536
	s_addc_u32 s7, s7, 0
	s_add_u32 s10, s10, 98304
	s_addc_u32 s11, s11, 0
	global_load_dwordx4 v[40:43], v8, s[4:5]
	global_load_dwordx4 v[72:75], v8, s[6:7]
	global_load_dwordx2 v[92:93], v9, s[10:11]
	s_add_u32 s4, s4, 65536
	s_addc_u32 s5, s5, 0
	s_add_u32 s6, s6, 65536
	s_addc_u32 s7, s7, 0
	s_add_u32 s10, s10, 98304
	s_addc_u32 s11, s11, 0
	global_load_dwordx4 v[44:47], v8, s[4:5]
	global_load_dwordx4 v[76:79], v8, s[6:7]
	global_load_dwordx2 v[94:95], v9, s[10:11]
	s_add_u32 s4, s4, 65536
	s_addc_u32 s5, s5, 0
	s_add_u32 s6, s6, 65536
	s_addc_u32 s7, s7, 0
	s_add_u32 s10, s10, 98304
	s_addc_u32 s11, s11, 0
	s_waitcnt vmcnt(21)
	v_lshlrev_b32_e32 v100, 16, v80
	v_and_b32_e32 v101, 0xffff0000, v80
	v_lshlrev_b32_e32 v102, 16, v81
	v_and_b32_e32 v103, 0xffff0000, v81
	v_add_f32_e32 v16, v16, v48
	v_add_f32_e32 v17, v17, v49
	v_add_f32_e32 v18, v18, v50
	v_add_f32_e32 v19, v19, v51
	v_fmac_f32_e32 v16, v176, v100
	v_fmac_f32_e32 v17, v177, v101
	v_fmac_f32_e32 v18, v178, v102
	v_fmac_f32_e32 v19, v179, v103
	v_mul_f32_e32 v104, v16, v16
	v_mul_f32_e32 v105, v17, v17
	v_mul_f32_e32 v106, v18, v18
	v_mul_f32_e32 v107, v19, v19
	v_fmaak_f32 v104, v1, v104, 0x40135761
	v_fmaak_f32 v105, v1, v105, 0x40135761
	v_fmaak_f32 v106, v1, v106, 0x40135761
	v_fmaak_f32 v107, v1, v107, 0x40135761
	v_mul_f32_e32 v104, v16, v104
	v_mul_f32_e32 v105, v17, v105
	v_mul_f32_e32 v106, v18, v106
	v_mul_f32_e32 v107, v19, v107
	v_exp_f32_e64 v104, -v104
	v_exp_f32_e64 v105, -v105
	v_exp_f32_e64 v106, -v106
	v_exp_f32_e64 v107, -v107
	v_add_f32_e32 v104, 1.0, v104
	v_add_f32_e32 v105, 1.0, v105
	v_add_f32_e32 v106, 1.0, v106
	v_add_f32_e32 v107, 1.0, v107
	v_rcp_f32_e32 v104, v104
	v_rcp_f32_e32 v105, v105
	v_rcp_f32_e32 v106, v106
	v_rcp_f32_e32 v107, v107
	v_mul_f32_e32 v16, v16, v104
	v_mul_f32_e32 v17, v17, v105
	v_mul_f32_e32 v18, v18, v106
	v_mul_f32_e32 v19, v19, v107
	v_cvt_pk_bf16_f32 v108, v16, v17
	v_cvt_pk_bf16_f32 v109, v18, v19
	global_store_dwordx2 v10, v[108:109], s[12:13]
	s_add_u32 s12, s12, 32768
	s_addc_u32 s13, s13, 0
	s_waitcnt vmcnt(19)
	v_lshlrev_b32_e32 v100, 16, v82
	v_and_b32_e32 v101, 0xffff0000, v82
	v_lshlrev_b32_e32 v102, 16, v83
	v_and_b32_e32 v103, 0xffff0000, v83
	v_add_f32_e32 v20, v20, v52
	v_add_f32_e32 v21, v21, v53
	v_add_f32_e32 v22, v22, v54
	v_add_f32_e32 v23, v23, v55
	v_fmac_f32_e32 v20, v176, v100
	v_fmac_f32_e32 v21, v177, v101
	v_fmac_f32_e32 v22, v178, v102
	v_fmac_f32_e32 v23, v179, v103
	v_mul_f32_e32 v104, v20, v20
	v_mul_f32_e32 v105, v21, v21
	v_mul_f32_e32 v106, v22, v22
	v_mul_f32_e32 v107, v23, v23
	v_fmaak_f32 v104, v1, v104, 0x40135761
	v_fmaak_f32 v105, v1, v105, 0x40135761
	v_fmaak_f32 v106, v1, v106, 0x40135761
	v_fmaak_f32 v107, v1, v107, 0x40135761
	v_mul_f32_e32 v104, v20, v104
	v_mul_f32_e32 v105, v21, v105
	v_mul_f32_e32 v106, v22, v106
	v_mul_f32_e32 v107, v23, v107
	v_exp_f32_e64 v104, -v104
	v_exp_f32_e64 v105, -v105
	v_exp_f32_e64 v106, -v106
	v_exp_f32_e64 v107, -v107
	v_add_f32_e32 v104, 1.0, v104
	v_add_f32_e32 v105, 1.0, v105
	v_add_f32_e32 v106, 1.0, v106
	v_add_f32_e32 v107, 1.0, v107
	v_rcp_f32_e32 v104, v104
	v_rcp_f32_e32 v105, v105
	v_rcp_f32_e32 v106, v106
	v_rcp_f32_e32 v107, v107
	v_mul_f32_e32 v20, v20, v104
	v_mul_f32_e32 v21, v21, v105
	v_mul_f32_e32 v22, v22, v106
	v_mul_f32_e32 v23, v23, v107
	v_cvt_pk_bf16_f32 v110, v20, v21
	v_cvt_pk_bf16_f32 v111, v22, v23
	global_store_dwordx2 v10, v[110:111], s[12:13]
	s_add_u32 s12, s12, 32768
	s_addc_u32 s13, s13, 0
	s_waitcnt vmcnt(17)
	v_lshlrev_b32_e32 v100, 16, v84
	v_and_b32_e32 v101, 0xffff0000, v84
	v_lshlrev_b32_e32 v102, 16, v85
	v_and_b32_e32 v103, 0xffff0000, v85
	v_add_f32_e32 v24, v24, v56
	v_add_f32_e32 v25, v25, v57
	v_add_f32_e32 v26, v26, v58
	v_add_f32_e32 v27, v27, v59
	v_fmac_f32_e32 v24, v176, v100
	v_fmac_f32_e32 v25, v177, v101
	v_fmac_f32_e32 v26, v178, v102
	v_fmac_f32_e32 v27, v179, v103
	v_mul_f32_e32 v104, v24, v24
	v_mul_f32_e32 v105, v25, v25
	v_mul_f32_e32 v106, v26, v26
	v_mul_f32_e32 v107, v27, v27
	v_fmaak_f32 v104, v1, v104, 0x40135761
	v_fmaak_f32 v105, v1, v105, 0x40135761
	v_fmaak_f32 v106, v1, v106, 0x40135761
	v_fmaak_f32 v107, v1, v107, 0x40135761
	v_mul_f32_e32 v104, v24, v104
	v_mul_f32_e32 v105, v25, v105
	v_mul_f32_e32 v106, v26, v106
	v_mul_f32_e32 v107, v27, v107
	v_exp_f32_e64 v104, -v104
	v_exp_f32_e64 v105, -v105
	v_exp_f32_e64 v106, -v106
	v_exp_f32_e64 v107, -v107
	v_add_f32_e32 v104, 1.0, v104
	v_add_f32_e32 v105, 1.0, v105
	v_add_f32_e32 v106, 1.0, v106
	v_add_f32_e32 v107, 1.0, v107
	v_rcp_f32_e32 v104, v104
	v_rcp_f32_e32 v105, v105
	v_rcp_f32_e32 v106, v106
	v_rcp_f32_e32 v107, v107
	v_mul_f32_e32 v24, v24, v104
	v_mul_f32_e32 v25, v25, v105
	v_mul_f32_e32 v26, v26, v106
	v_mul_f32_e32 v27, v27, v107
	v_cvt_pk_bf16_f32 v108, v24, v25
	v_cvt_pk_bf16_f32 v109, v26, v27
	global_store_dwordx2 v10, v[108:109], s[12:13]
	s_add_u32 s12, s12, 32768
	s_addc_u32 s13, s13, 0
	s_waitcnt vmcnt(15)
	v_lshlrev_b32_e32 v100, 16, v86
	v_and_b32_e32 v101, 0xffff0000, v86
	v_lshlrev_b32_e32 v102, 16, v87
	v_and_b32_e32 v103, 0xffff0000, v87
	v_add_f32_e32 v28, v28, v60
	v_add_f32_e32 v29, v29, v61
	v_add_f32_e32 v30, v30, v62
	v_add_f32_e32 v31, v31, v63
	v_fmac_f32_e32 v28, v176, v100
	v_fmac_f32_e32 v29, v177, v101
	v_fmac_f32_e32 v30, v178, v102
	v_fmac_f32_e32 v31, v179, v103
	v_mul_f32_e32 v104, v28, v28
	v_mul_f32_e32 v105, v29, v29
	v_mul_f32_e32 v106, v30, v30
	v_mul_f32_e32 v107, v31, v31
	v_fmaak_f32 v104, v1, v104, 0x40135761
	v_fmaak_f32 v105, v1, v105, 0x40135761
	v_fmaak_f32 v106, v1, v106, 0x40135761
	v_fmaak_f32 v107, v1, v107, 0x40135761
	v_mul_f32_e32 v104, v28, v104
	v_mul_f32_e32 v105, v29, v105
	v_mul_f32_e32 v106, v30, v106
	v_mul_f32_e32 v107, v31, v107
	v_exp_f32_e64 v104, -v104
	v_exp_f32_e64 v105, -v105
	v_exp_f32_e64 v106, -v106
	v_exp_f32_e64 v107, -v107
	v_add_f32_e32 v104, 1.0, v104
	v_add_f32_e32 v105, 1.0, v105
	v_add_f32_e32 v106, 1.0, v106
	v_add_f32_e32 v107, 1.0, v107
	v_rcp_f32_e32 v104, v104
	v_rcp_f32_e32 v105, v105
	v_rcp_f32_e32 v106, v106
	v_rcp_f32_e32 v107, v107
	v_mul_f32_e32 v28, v28, v104
	v_mul_f32_e32 v29, v29, v105
	v_mul_f32_e32 v30, v30, v106
	v_mul_f32_e32 v31, v31, v107
	v_cvt_pk_bf16_f32 v110, v28, v29
	v_cvt_pk_bf16_f32 v111, v30, v31
	global_store_dwordx2 v10, v[110:111], s[12:13]
	s_add_u32 s12, s12, 32768
	s_addc_u32 s13, s13, 0
	s_waitcnt vmcnt(13)
	v_lshlrev_b32_e32 v100, 16, v88
	v_and_b32_e32 v101, 0xffff0000, v88
	v_lshlrev_b32_e32 v102, 16, v89
	v_and_b32_e32 v103, 0xffff0000, v89
	v_add_f32_e32 v32, v32, v64
	v_add_f32_e32 v33, v33, v65
	v_add_f32_e32 v34, v34, v66
	v_add_f32_e32 v35, v35, v67
	v_fmac_f32_e32 v32, v176, v100
	v_fmac_f32_e32 v33, v177, v101
	v_fmac_f32_e32 v34, v178, v102
	v_fmac_f32_e32 v35, v179, v103
	v_mul_f32_e32 v104, v32, v32
	v_mul_f32_e32 v105, v33, v33
	v_mul_f32_e32 v106, v34, v34
	v_mul_f32_e32 v107, v35, v35
	v_fmaak_f32 v104, v1, v104, 0x40135761
	v_fmaak_f32 v105, v1, v105, 0x40135761
	v_fmaak_f32 v106, v1, v106, 0x40135761
	v_fmaak_f32 v107, v1, v107, 0x40135761
	v_mul_f32_e32 v104, v32, v104
	v_mul_f32_e32 v105, v33, v105
	v_mul_f32_e32 v106, v34, v106
	v_mul_f32_e32 v107, v35, v107
	v_exp_f32_e64 v104, -v104
	v_exp_f32_e64 v105, -v105
	v_exp_f32_e64 v106, -v106
	v_exp_f32_e64 v107, -v107
	v_add_f32_e32 v104, 1.0, v104
	v_add_f32_e32 v105, 1.0, v105
	v_add_f32_e32 v106, 1.0, v106
	v_add_f32_e32 v107, 1.0, v107
	v_rcp_f32_e32 v104, v104
	v_rcp_f32_e32 v105, v105
	v_rcp_f32_e32 v106, v106
	v_rcp_f32_e32 v107, v107
	v_mul_f32_e32 v32, v32, v104
	v_mul_f32_e32 v33, v33, v105
	v_mul_f32_e32 v34, v34, v106
	v_mul_f32_e32 v35, v35, v107
	v_cvt_pk_bf16_f32 v108, v32, v33
	v_cvt_pk_bf16_f32 v109, v34, v35
	global_store_dwordx2 v10, v[108:109], s[12:13]
	s_add_u32 s12, s12, 32768
	s_addc_u32 s13, s13, 0
	s_waitcnt vmcnt(11)
	v_lshlrev_b32_e32 v100, 16, v90
	v_and_b32_e32 v101, 0xffff0000, v90
	v_lshlrev_b32_e32 v102, 16, v91
	v_and_b32_e32 v103, 0xffff0000, v91
	v_add_f32_e32 v36, v36, v68
	v_add_f32_e32 v37, v37, v69
	v_add_f32_e32 v38, v38, v70
	v_add_f32_e32 v39, v39, v71
	v_fmac_f32_e32 v36, v176, v100
	v_fmac_f32_e32 v37, v177, v101
	v_fmac_f32_e32 v38, v178, v102
	v_fmac_f32_e32 v39, v179, v103
	v_mul_f32_e32 v104, v36, v36
	v_mul_f32_e32 v105, v37, v37
	v_mul_f32_e32 v106, v38, v38
	v_mul_f32_e32 v107, v39, v39
	v_fmaak_f32 v104, v1, v104, 0x40135761
	v_fmaak_f32 v105, v1, v105, 0x40135761
	v_fmaak_f32 v106, v1, v106, 0x40135761
	v_fmaak_f32 v107, v1, v107, 0x40135761
	v_mul_f32_e32 v104, v36, v104
	v_mul_f32_e32 v105, v37, v105
	v_mul_f32_e32 v106, v38, v106
	v_mul_f32_e32 v107, v39, v107
	v_exp_f32_e64 v104, -v104
	v_exp_f32_e64 v105, -v105
	v_exp_f32_e64 v106, -v106
	v_exp_f32_e64 v107, -v107
	v_add_f32_e32 v104, 1.0, v104
	v_add_f32_e32 v105, 1.0, v105
	v_add_f32_e32 v106, 1.0, v106
	v_add_f32_e32 v107, 1.0, v107
	v_rcp_f32_e32 v104, v104
	v_rcp_f32_e32 v105, v105
	v_rcp_f32_e32 v106, v106
	v_rcp_f32_e32 v107, v107
	v_mul_f32_e32 v36, v36, v104
	v_mul_f32_e32 v37, v37, v105
	v_mul_f32_e32 v38, v38, v106
	v_mul_f32_e32 v39, v39, v107
	v_cvt_pk_bf16_f32 v110, v36, v37
	v_cvt_pk_bf16_f32 v111, v38, v39
	global_store_dwordx2 v10, v[110:111], s[12:13]
	s_add_u32 s12, s12, 32768
	s_addc_u32 s13, s13, 0
	s_waitcnt vmcnt(9)
	v_lshlrev_b32_e32 v100, 16, v92
	v_and_b32_e32 v101, 0xffff0000, v92
	v_lshlrev_b32_e32 v102, 16, v93
	v_and_b32_e32 v103, 0xffff0000, v93
	v_add_f32_e32 v40, v40, v72
	v_add_f32_e32 v41, v41, v73
	v_add_f32_e32 v42, v42, v74
	v_add_f32_e32 v43, v43, v75
	v_fmac_f32_e32 v40, v176, v100
	v_fmac_f32_e32 v41, v177, v101
	v_fmac_f32_e32 v42, v178, v102
	v_fmac_f32_e32 v43, v179, v103
	v_mul_f32_e32 v104, v40, v40
	v_mul_f32_e32 v105, v41, v41
	v_mul_f32_e32 v106, v42, v42
	v_mul_f32_e32 v107, v43, v43
	v_fmaak_f32 v104, v1, v104, 0x40135761
	v_fmaak_f32 v105, v1, v105, 0x40135761
	v_fmaak_f32 v106, v1, v106, 0x40135761
	v_fmaak_f32 v107, v1, v107, 0x40135761
	v_mul_f32_e32 v104, v40, v104
	v_mul_f32_e32 v105, v41, v105
	v_mul_f32_e32 v106, v42, v106
	v_mul_f32_e32 v107, v43, v107
	v_exp_f32_e64 v104, -v104
	v_exp_f32_e64 v105, -v105
	v_exp_f32_e64 v106, -v106
	v_exp_f32_e64 v107, -v107
	v_add_f32_e32 v104, 1.0, v104
	v_add_f32_e32 v105, 1.0, v105
	v_add_f32_e32 v106, 1.0, v106
	v_add_f32_e32 v107, 1.0, v107
	v_rcp_f32_e32 v104, v104
	v_rcp_f32_e32 v105, v105
	v_rcp_f32_e32 v106, v106
	v_rcp_f32_e32 v107, v107
	v_mul_f32_e32 v40, v40, v104
	v_mul_f32_e32 v41, v41, v105
	v_mul_f32_e32 v42, v42, v106
	v_mul_f32_e32 v43, v43, v107
	v_cvt_pk_bf16_f32 v108, v40, v41
	v_cvt_pk_bf16_f32 v109, v42, v43
	global_store_dwordx2 v10, v[108:109], s[12:13]
	s_add_u32 s12, s12, 32768
	s_addc_u32 s13, s13, 0
	s_waitcnt vmcnt(7)
	v_lshlrev_b32_e32 v100, 16, v94
	v_and_b32_e32 v101, 0xffff0000, v94
	v_lshlrev_b32_e32 v102, 16, v95
	v_and_b32_e32 v103, 0xffff0000, v95
	v_add_f32_e32 v44, v44, v76
	v_add_f32_e32 v45, v45, v77
	v_add_f32_e32 v46, v46, v78
	v_add_f32_e32 v47, v47, v79
	v_fmac_f32_e32 v44, v176, v100
	v_fmac_f32_e32 v45, v177, v101
	v_fmac_f32_e32 v46, v178, v102
	v_fmac_f32_e32 v47, v179, v103
	v_mul_f32_e32 v104, v44, v44
	v_mul_f32_e32 v105, v45, v45
	v_mul_f32_e32 v106, v46, v46
	v_mul_f32_e32 v107, v47, v47
	v_fmaak_f32 v104, v1, v104, 0x40135761
	v_fmaak_f32 v105, v1, v105, 0x40135761
	v_fmaak_f32 v106, v1, v106, 0x40135761
	v_fmaak_f32 v107, v1, v107, 0x40135761
	v_mul_f32_e32 v104, v44, v104
	v_mul_f32_e32 v105, v45, v105
	v_mul_f32_e32 v106, v46, v106
	v_mul_f32_e32 v107, v47, v107
	v_exp_f32_e64 v104, -v104
	v_exp_f32_e64 v105, -v105
	v_exp_f32_e64 v106, -v106
	v_exp_f32_e64 v107, -v107
	v_add_f32_e32 v104, 1.0, v104
	v_add_f32_e32 v105, 1.0, v105
	v_add_f32_e32 v106, 1.0, v106
	v_add_f32_e32 v107, 1.0, v107
	v_rcp_f32_e32 v104, v104
	v_rcp_f32_e32 v105, v105
	v_rcp_f32_e32 v106, v106
	v_rcp_f32_e32 v107, v107
	v_mul_f32_e32 v44, v44, v104
	v_mul_f32_e32 v45, v45, v105
	v_mul_f32_e32 v46, v46, v106
	v_mul_f32_e32 v47, v47, v107
	v_cvt_pk_bf16_f32 v110, v44, v45
	v_cvt_pk_bf16_f32 v111, v46, v47
	global_store_dwordx2 v10, v[110:111], s[12:13]
	s_add_u32 s12, s12, 32768
	s_addc_u32 s13, s13, 0
	s_add_u32 s14, s14, 8
	s_cmp_lt_u32 s14, 32
	s_cbranch_scc1 .Lssm_comb
	s_branch .Lssm_done
.Lssm_ctx:
	s_and_b32 s22, s89, 1
	s_lshr_b32 s26, s89, 2
	s_lshl_b32 s26, s26, 1
	s_or_b32 s22, s22, s26
	s_lshl_b32 s21, s22, 14
	s_add_u32 s21, s21, 0x11000
	s_lshl_b32 s26, s2, 2
	s_add_u32 s22, s22, s26
	s_and_b32 s24, s22, 63
	s_lshr_b32 s23, s22, 6
	s_lshl_b32 s23, s23, 1
	s_lshl_b32 s25, s23, 8
	v_and_b32_e32 v6, 31, v191
	v_lshrrev_b32_e32 v7, 5, v191
	v_and_b32_e32 v8, 15, v191
	v_lshrrev_b32_e32 v9, 4, v191
	v_lshrrev_b32_e32 v10, 3, v6
	v_lshlrev_b32_e32 v10, 10, v10
	v_and_b32_e32 v11, 7, v6
	v_lshl_add_u32 v10, v11, 5, v10
	v_lshl_add_u32 v10, v7, 8, v10
	s_add_u32 s28, s24, 0
	s_lshl_b32 s29, s28, 13
	s_add_u32 s29, s29, 0x200000
	s_add_u32 s10, s62, s29
	s_addc_u32 s11, s63, 0
	s_add_u32 s12, s10, 0x1000
	s_addc_u32 s13, s11, 0
	global_load_dwordx4 v[88:91], v10, s[10:11]
	global_load_dwordx4 v[92:95], v10, s[10:11] offset:16
	global_load_dwordx4 v[96:99], v10, s[12:13]
	global_load_dwordx4 v[100:103], v10, s[12:13] offset:16
	s_lshl_b32 s29, s28, 12
	s_add_u32 s29, s29, 0x300000
	s_add_u32 s16, s62, s29
	s_addc_u32 s17, s63, 0
	v_lshlrev_b32_e32 v10, 4, v191
	global_load_dwordx4 v[104:107], v10, s[16:17]
	global_load_dwordx4 v[108:111], v10, s[16:17] offset:1024
	global_load_dwordx4 v[112:115], v10, s[16:17] offset:2048
	global_load_dwordx4 v[116:119], v10, s[16:17] offset:3072
	s_lshl_b32 s29, s28, 9
	s_add_u32 s29, s29, 0x100000
	s_add_u32 s18, s62, s29
	s_addc_u32 s19, s63, 0
	v_lshlrev_b32_e32 v10, 3, v6
	global_load_dwordx2 v[120:121], v10, s[18:19]
	global_load_dwordx2 v[122:123], v10, s[18:19] offset:256
	s_lshl_b32 s30, s23, 1
	s_lshl_b32 s30, s30, 15
	s_lshl_b32 s31, s24, 8
	s_add_u32 s30, s30, s31
	v_lshlrev_b32_e32 v10, 16, v7
	v_lshl_add_u32 v10, v6, 2, v10
	v_mov_b32_e32 v196, v10
	v_mov_b32_e32 v126, 0
	v_mov_b32_e32 v127, 0
	v_mov_b32_e32 v128, 0
	v_mov_b32_e32 v129, 0
	s_mul_i32 s31, s25, 0x1800
	s_lshl_b32 s29, s24, 5
	s_add_u32 s31, s31, s29
	s_add_u32 s31, s31, 0x8801000
	s_add_u32 s4, s62, s31
	s_addc_u32 s5, s63, 0
	v_lshrrev_b32_e32 v10, 3, v6
	v_and_b32_e32 v11, 3, v6
	v_lshl_add_u32 v10, v10, 2, v11
	v_mul_u32_u24_e32 v10, 0x1800, v10
	v_lshl_add_u32 v10, v7, 4, v10
	v_bfe_u32 v11, v6, 2, 1
	v_mul_u32_u24_e32 v11, 1572864, v11
	v_add_u32_e32 v186, v10, v11
	v_mul_u32_u24_e32 v10, 0x1100, v7
	v_lshl_add_u32 v10, v6, 2, v10
	v_add_u32_e32 v14, s20, v10
	v_add_u32_e32 v15, 1088, v14
	v_add_u32_e32 v184, 2176, v14
	v_add_u32_e32 v185, 3264, v14
	v_mul_u32_u24_e32 v10, 0x110, v8
	v_lshl_add_u32 v10, v9, 4, v10
	v_add_u32_e32 v187, s20, v10
	v_lshlrev_b32_e32 v10, 5, v8
	v_lshl_add_u32 v10, v9, 3, v10
	v_add_u32_e32 v188, s21, v10
	v_add_u32_e32 v189, 0x2000, v188
	s_add_u32 s34, s4, 0
	s_addc_u32 s35, s5, 0
	global_load_dwordx4 v[80:83], v186, s[34:35]
	s_mov_b64 s[10:11], s[34:35]
	s_add_u32 s10, s10, 98304
	s_addc_u32 s11, s11, 0
	global_load_dwordx4 v[84:87], v186, s[10:11]
	s_mov_b64 s[34:35], s[10:11]
	s_add_u32 s10, s10, 98304
	s_addc_u32 s11, s11, 0
	s_mov_b32 s36, 0
	s_mov_b32 s14, 0
	s_waitcnt vmcnt(0)
	v_xor_b32_e32 v124, 0x80000000, v121
	v_xor_b32_e32 v125, 0x80000000, v123
	v_add_u32_e32 v193, s36, v188
	v_add_u32_e32 v194, s36, v189

.Lssm_sk1_d0m1:
	s_waitcnt vmcnt(1)
	v_mfma_f32_32x32x16_bf16 v[16:31], v[80:83], v[88:91], 0
	v_mfma_f32_32x32x16_bf16 v[32:47], v[80:83], v[92:95], 0
	v_mfma_f32_32x32x16_bf16 v[48:63], v[80:83], v[96:99], 0
	v_mfma_f32_32x32x16_bf16 v[64:79], v[80:83], v[100:103], 0
	s_cmp_eq_u32 s14, 0
	s_cbranch_scc1 .Lssm_sk3_d0m1
	s_waitcnt lgkmcnt(0)
	v_mfma_f32_16x16x32_bf16 v[162:165], v[104:107], v[130:133], 0
	v_mfma_f32_16x16x32_bf16 v[166:169], v[104:107], v[146:149], 0
	v_mfma_f32_16x16x32_bf16 v[162:165], v[108:111], v[134:137], v[162:165]
	v_mfma_f32_16x16x32_bf16 v[166:169], v[108:111], v[150:153], v[166:169]
	v_mfma_f32_16x16x32_bf16 v[162:165], v[112:115], v[138:141], v[162:165]
	v_mfma_f32_16x16x32_bf16 v[166:169], v[112:115], v[154:157], v[166:169]
	v_mfma_f32_16x16x32_bf16 v[162:165], v[116:119], v[142:145], v[162:165]
	v_mfma_f32_16x16x32_bf16 v[166:169], v[116:119], v[158:161], v[166:169]
	s_nop 7
	v_cvt_pk_bf16_f32 v6, v162, v163
	v_cvt_pk_bf16_f32 v7, v164, v165
	ds_write_b64 v193, v[6:7]
	v_cvt_pk_bf16_f32 v6, v166, v167
	v_cvt_pk_bf16_f32 v7, v168, v169
	ds_write_b64 v194, v[6:7]
	s_add_u32 s36, s36, 512
	v_add_u32_e32 v193, s36, v188
	v_add_u32_e32 v194, s36, v189
.Lssm_sk3_d0m1:
	s_nop 9
	global_load_dwordx4 v[80:83], v186, s[10:11]
	s_add_u32 s34, s34, 98304
	s_addc_u32 s35, s35, 0
	s_add_u32 s10, s10, 98304
	s_addc_u32 s11, s11, 0
	v_fmac_f32_e32 v16, v120, v126
	v_fmac_f32_e32 v32, v120, v127
	v_fmac_f32_e32 v48, v122, v128
	v_fmac_f32_e32 v64, v122, v129
	v_fmac_f32_e32 v16, v124, v127
	v_fmac_f32_e32 v32, v121, v126
	v_fmac_f32_e32 v48, v125, v129
	v_fmac_f32_e32 v64, v123, v128
	v_cvt_pk_bf16_f32 v170, v16, v32
	v_cvt_pk_bf16_f32 v171, v48, v64
	ds_write2_b32 v14, v170, v171 offset1:32
	v_fmac_f32_e32 v17, v120, v16
	v_fmac_f32_e32 v33, v120, v32
	v_fmac_f32_e32 v49, v122, v48
	v_fmac_f32_e32 v65, v122, v64
	v_fmac_f32_e32 v17, v124, v32
	v_fmac_f32_e32 v33, v121, v16
	v_fmac_f32_e32 v49, v125, v64
	v_fmac_f32_e32 v65, v123, v48
	v_cvt_pk_bf16_f32 v170, v17, v33
	v_cvt_pk_bf16_f32 v171, v49, v65
	ds_write2_b32 v14, v170, v171 offset0:68 offset1:100
	v_fmac_f32_e32 v18, v120, v17
	v_fmac_f32_e32 v34, v120, v33
	v_fmac_f32_e32 v50, v122, v49
	v_fmac_f32_e32 v66, v122, v65
	v_fmac_f32_e32 v18, v124, v33
	v_fmac_f32_e32 v34, v121, v17
	v_fmac_f32_e32 v50, v125, v65
	v_fmac_f32_e32 v66, v123, v49
	v_cvt_pk_bf16_f32 v170, v18, v34
	v_cvt_pk_bf16_f32 v171, v50, v66
	ds_write2_b32 v14, v170, v171 offset0:136 offset1:168
	v_fmac_f32_e32 v19, v120, v18
	v_fmac_f32_e32 v35, v120, v34
	v_fmac_f32_e32 v51, v122, v50
	v_fmac_f32_e32 v67, v122, v66
	v_fmac_f32_e32 v19, v124, v34
	v_fmac_f32_e32 v35, v121, v18
	v_fmac_f32_e32 v51, v125, v66
	v_fmac_f32_e32 v67, v123, v50
	v_cvt_pk_bf16_f32 v170, v19, v35
	v_cvt_pk_bf16_f32 v171, v51, v67
	ds_write2_b32 v14, v170, v171 offset0:204 offset1:236
	v_fmac_f32_e32 v20, v120, v19
	v_fmac_f32_e32 v36, v120, v35
	v_fmac_f32_e32 v52, v122, v51
	v_fmac_f32_e32 v68, v122, v67
	v_fmac_f32_e32 v20, v124, v35
	v_fmac_f32_e32 v36, v121, v19
	v_fmac_f32_e32 v52, v125, v67
	v_fmac_f32_e32 v68, v123, v51
	v_cvt_pk_bf16_f32 v170, v20, v36
	v_cvt_pk_bf16_f32 v171, v52, v68
	ds_write2_b32 v15, v170, v171 offset1:32
	v_fmac_f32_e32 v21, v120, v20
	v_fmac_f32_e32 v37, v120, v36
	v_fmac_f32_e32 v53, v122, v52
	v_fmac_f32_e32 v69, v122, v68
	v_fmac_f32_e32 v21, v124, v36
	v_fmac_f32_e32 v37, v121, v20
	v_fmac_f32_e32 v53, v125, v68
	v_fmac_f32_e32 v69, v123, v52
	v_cvt_pk_bf16_f32 v170, v21, v37
	v_cvt_pk_bf16_f32 v171, v53, v69
	ds_write2_b32 v15, v170, v171 offset0:68 offset1:100
	v_fmac_f32_e32 v22, v120, v21
	v_fmac_f32_e32 v38, v120, v37
	v_fmac_f32_e32 v54, v122, v53
	v_fmac_f32_e32 v70, v122, v69
	v_fmac_f32_e32 v22, v124, v37
	v_fmac_f32_e32 v38, v121, v21
	v_fmac_f32_e32 v54, v125, v69
	v_fmac_f32_e32 v70, v123, v53
	v_cvt_pk_bf16_f32 v170, v22, v38
	v_cvt_pk_bf16_f32 v171, v54, v70
	ds_write2_b32 v15, v170, v171 offset0:136 offset1:168
	v_fmac_f32_e32 v23, v120, v22
	v_fmac_f32_e32 v39, v120, v38
	v_fmac_f32_e32 v55, v122, v54
	v_fmac_f32_e32 v71, v122, v70
	v_fmac_f32_e32 v23, v124, v38
	v_fmac_f32_e32 v39, v121, v22
	v_fmac_f32_e32 v55, v125, v70
	v_fmac_f32_e32 v71, v123, v54
	v_cvt_pk_bf16_f32 v170, v23, v39
	v_cvt_pk_bf16_f32 v171, v55, v71
	ds_write2_b32 v15, v170, v171 offset0:204 offset1:236
	v_fmac_f32_e32 v24, v120, v23
	v_fmac_f32_e32 v40, v120, v39
	v_fmac_f32_e32 v56, v122, v55
	v_fmac_f32_e32 v72, v122, v71
	v_fmac_f32_e32 v24, v124, v39
	v_fmac_f32_e32 v40, v121, v23
	v_fmac_f32_e32 v56, v125, v71
	v_fmac_f32_e32 v72, v123, v55
	v_cvt_pk_bf16_f32 v170, v24, v40
	v_cvt_pk_bf16_f32 v171, v56, v72
	ds_write2_b32 v184, v170, v171 offset1:32
	v_fmac_f32_e32 v25, v120, v24
	v_fmac_f32_e32 v41, v120, v40
	v_fmac_f32_e32 v57, v122, v56
	v_fmac_f32_e32 v73, v122, v72
	v_fmac_f32_e32 v25, v124, v40
	v_fmac_f32_e32 v41, v121, v24
	v_fmac_f32_e32 v57, v125, v72
	v_fmac_f32_e32 v73, v123, v56
	v_cvt_pk_bf16_f32 v170, v25, v41
	v_cvt_pk_bf16_f32 v171, v57, v73
	ds_write2_b32 v184, v170, v171 offset0:68 offset1:100
	v_fmac_f32_e32 v26, v120, v25
	v_fmac_f32_e32 v42, v120, v41
	v_fmac_f32_e32 v58, v122, v57
	v_fmac_f32_e32 v74, v122, v73
	v_fmac_f32_e32 v26, v124, v41
	v_fmac_f32_e32 v42, v121, v25
	v_fmac_f32_e32 v58, v125, v73
	v_fmac_f32_e32 v74, v123, v57
	v_cvt_pk_bf16_f32 v170, v26, v42
	v_cvt_pk_bf16_f32 v171, v58, v74
	ds_write2_b32 v184, v170, v171 offset0:136 offset1:168
	v_fmac_f32_e32 v27, v120, v26
	v_fmac_f32_e32 v43, v120, v42
	v_fmac_f32_e32 v59, v122, v58
	v_fmac_f32_e32 v75, v122, v74
	v_fmac_f32_e32 v27, v124, v42
	v_fmac_f32_e32 v43, v121, v26
	v_fmac_f32_e32 v59, v125, v74
	v_fmac_f32_e32 v75, v123, v58
	v_cvt_pk_bf16_f32 v170, v27, v43
	v_cvt_pk_bf16_f32 v171, v59, v75
	ds_write2_b32 v184, v170, v171 offset0:204 offset1:236
	v_fmac_f32_e32 v28, v120, v27
	v_fmac_f32_e32 v44, v120, v43
	v_fmac_f32_e32 v60, v122, v59
	v_fmac_f32_e32 v76, v122, v75
	v_fmac_f32_e32 v28, v124, v43
	v_fmac_f32_e32 v44, v121, v27
	v_fmac_f32_e32 v60, v125, v75
	v_fmac_f32_e32 v76, v123, v59
	v_cvt_pk_bf16_f32 v170, v28, v44
	v_cvt_pk_bf16_f32 v171, v60, v76
	ds_write2_b32 v185, v170, v171 offset1:32
	v_fmac_f32_e32 v29, v120, v28
	v_fmac_f32_e32 v45, v120, v44
	v_fmac_f32_e32 v61, v122, v60
	v_fmac_f32_e32 v77, v122, v76
	v_fmac_f32_e32 v29, v124, v44
	v_fmac_f32_e32 v45, v121, v28
	v_fmac_f32_e32 v61, v125, v76
	v_fmac_f32_e32 v77, v123, v60
	v_cvt_pk_bf16_f32 v170, v29, v45
	v_cvt_pk_bf16_f32 v171, v61, v77
	ds_write2_b32 v185, v170, v171 offset0:68 offset1:100
	v_fmac_f32_e32 v30, v120, v29
	v_fmac_f32_e32 v46, v120, v45
	v_fmac_f32_e32 v62, v122, v61
	v_fmac_f32_e32 v78, v122, v77
	v_fmac_f32_e32 v30, v124, v45
	v_fmac_f32_e32 v46, v121, v29
	v_fmac_f32_e32 v62, v125, v77
	v_fmac_f32_e32 v78, v123, v61
	v_cvt_pk_bf16_f32 v170, v30, v46
	v_cvt_pk_bf16_f32 v171, v62, v78
	ds_write2_b32 v185, v170, v171 offset0:136 offset1:168
	v_fmac_f32_e32 v31, v120, v30
	v_fmac_f32_e32 v47, v120, v46
	v_fmac_f32_e32 v63, v122, v62
	v_fmac_f32_e32 v79, v122, v78
	v_fmac_f32_e32 v31, v124, v46
	v_fmac_f32_e32 v47, v121, v30
	v_fmac_f32_e32 v63, v125, v78
	v_fmac_f32_e32 v79, v123, v62
	v_cvt_pk_bf16_f32 v170, v31, v47
	v_cvt_pk_bf16_f32 v171, v63, v79
	ds_write2_b32 v185, v170, v171 offset0:204 offset1:236
	v_mov_b32_e32 v126, v31
	v_mov_b32_e32 v127, v47
	v_mov_b32_e32 v128, v63
	v_mov_b32_e32 v129, v79
	ds_read_b128 v[130:133], v187
	ds_read_b128 v[134:137], v187 offset:64
	ds_read_b128 v[138:141], v187 offset:128
	ds_read_b128 v[142:145], v187 offset:192
	ds_read_b128 v[146:149], v187 offset:4352
	ds_read_b128 v[150:153], v187 offset:4416
	ds_read_b128 v[154:157], v187 offset:4480
	ds_read_b128 v[158:161], v187 offset:4544
	s_waitcnt vmcnt(1)
	v_mfma_f32_32x32x16_bf16 v[16:31], v[84:87], v[88:91], 0
	v_mfma_f32_32x32x16_bf16 v[32:47], v[84:87], v[92:95], 0
	v_mfma_f32_32x32x16_bf16 v[48:63], v[84:87], v[96:99], 0
	v_mfma_f32_32x32x16_bf16 v[64:79], v[84:87], v[100:103], 0
	s_waitcnt lgkmcnt(0)
	v_mfma_f32_16x16x32_bf16 v[162:165], v[104:107], v[130:133], 0
	v_mfma_f32_16x16x32_bf16 v[166:169], v[104:107], v[146:149], 0
	v_mfma_f32_16x16x32_bf16 v[162:165], v[108:111], v[134:137], v[162:165]
	v_mfma_f32_16x16x32_bf16 v[166:169], v[108:111], v[150:153], v[166:169]
	v_mfma_f32_16x16x32_bf16 v[162:165], v[112:115], v[138:141], v[162:165]
	v_mfma_f32_16x16x32_bf16 v[166:169], v[112:115], v[154:157], v[166:169]
	v_mfma_f32_16x16x32_bf16 v[162:165], v[116:119], v[142:145], v[162:165]
	v_mfma_f32_16x16x32_bf16 v[166:169], v[116:119], v[158:161], v[166:169]
	s_nop 7
	v_cvt_pk_bf16_f32 v6, v162, v163
	v_cvt_pk_bf16_f32 v7, v164, v165
	ds_write_b64 v193, v[6:7]
	v_cvt_pk_bf16_f32 v6, v166, v167
	v_cvt_pk_bf16_f32 v7, v168, v169
	ds_write_b64 v194, v[6:7]
	s_add_u32 s36, s36, 512
	v_add_u32_e32 v193, s36, v188
	v_add_u32_e32 v194, s36, v189
	global_load_dwordx4 v[84:87], v186, s[10:11]
	s_add_u32 s34, s34, 98304
	s_addc_u32 s35, s35, 0
	s_add_u32 s10, s10, 98304
	s_addc_u32 s11, s11, 0
	v_fmac_f32_e32 v16, v120, v126
	v_fmac_f32_e32 v32, v120, v127
	v_fmac_f32_e32 v48, v122, v128
	v_fmac_f32_e32 v64, v122, v129
	v_fmac_f32_e32 v16, v124, v127
	v_fmac_f32_e32 v32, v121, v126
	v_fmac_f32_e32 v48, v125, v129
	v_fmac_f32_e32 v64, v123, v128
	v_cvt_pk_bf16_f32 v170, v16, v32
	v_cvt_pk_bf16_f32 v171, v48, v64
	ds_write2_b32 v14, v170, v171 offset1:32
	v_fmac_f32_e32 v17, v120, v16
	v_fmac_f32_e32 v33, v120, v32
	v_fmac_f32_e32 v49, v122, v48
	v_fmac_f32_e32 v65, v122, v64
	v_fmac_f32_e32 v17, v124, v32
	v_fmac_f32_e32 v33, v121, v16
	v_fmac_f32_e32 v49, v125, v64
	v_fmac_f32_e32 v65, v123, v48
	v_cvt_pk_bf16_f32 v170, v17, v33
	v_cvt_pk_bf16_f32 v171, v49, v65
	ds_write2_b32 v14, v170, v171 offset0:68 offset1:100
	v_fmac_f32_e32 v18, v120, v17
	v_fmac_f32_e32 v34, v120, v33
	v_fmac_f32_e32 v50, v122, v49
	v_fmac_f32_e32 v66, v122, v65
	v_fmac_f32_e32 v18, v124, v33
	v_fmac_f32_e32 v34, v121, v17
	v_fmac_f32_e32 v50, v125, v65
	v_fmac_f32_e32 v66, v123, v49
	v_cvt_pk_bf16_f32 v170, v18, v34
	v_cvt_pk_bf16_f32 v171, v50, v66
	ds_write2_b32 v14, v170, v171 offset0:136 offset1:168
	v_fmac_f32_e32 v19, v120, v18
	v_fmac_f32_e32 v35, v120, v34
	v_fmac_f32_e32 v51, v122, v50
	v_fmac_f32_e32 v67, v122, v66
	v_fmac_f32_e32 v19, v124, v34
	v_fmac_f32_e32 v35, v121, v18
	v_fmac_f32_e32 v51, v125, v66
	v_fmac_f32_e32 v67, v123, v50
	v_cvt_pk_bf16_f32 v170, v19, v35
	v_cvt_pk_bf16_f32 v171, v51, v67
	ds_write2_b32 v14, v170, v171 offset0:204 offset1:236
	v_fmac_f32_e32 v20, v120, v19
	v_fmac_f32_e32 v36, v120, v35
	v_fmac_f32_e32 v52, v122, v51
	v_fmac_f32_e32 v68, v122, v67
	v_fmac_f32_e32 v20, v124, v35
	v_fmac_f32_e32 v36, v121, v19
	v_fmac_f32_e32 v52, v125, v67
	v_fmac_f32_e32 v68, v123, v51
	v_cvt_pk_bf16_f32 v170, v20, v36
	v_cvt_pk_bf16_f32 v171, v52, v68
	ds_write2_b32 v15, v170, v171 offset1:32
	v_fmac_f32_e32 v21, v120, v20
	v_fmac_f32_e32 v37, v120, v36
	v_fmac_f32_e32 v53, v122, v52
	v_fmac_f32_e32 v69, v122, v68
	v_fmac_f32_e32 v21, v124, v36
	v_fmac_f32_e32 v37, v121, v20
	v_fmac_f32_e32 v53, v125, v68
	v_fmac_f32_e32 v69, v123, v52
	v_cvt_pk_bf16_f32 v170, v21, v37
	v_cvt_pk_bf16_f32 v171, v53, v69
	ds_write2_b32 v15, v170, v171 offset0:68 offset1:100
	v_fmac_f32_e32 v22, v120, v21
	v_fmac_f32_e32 v38, v120, v37
	v_fmac_f32_e32 v54, v122, v53
	v_fmac_f32_e32 v70, v122, v69
	v_fmac_f32_e32 v22, v124, v37
	v_fmac_f32_e32 v38, v121, v21
	v_fmac_f32_e32 v54, v125, v69
	v_fmac_f32_e32 v70, v123, v53
	v_cvt_pk_bf16_f32 v170, v22, v38
	v_cvt_pk_bf16_f32 v171, v54, v70
	ds_write2_b32 v15, v170, v171 offset0:136 offset1:168
	v_fmac_f32_e32 v23, v120, v22
	v_fmac_f32_e32 v39, v120, v38
	v_fmac_f32_e32 v55, v122, v54
	v_fmac_f32_e32 v71, v122, v70
	v_fmac_f32_e32 v23, v124, v38
	v_fmac_f32_e32 v39, v121, v22
	v_fmac_f32_e32 v55, v125, v70
	v_fmac_f32_e32 v71, v123, v54
	v_cvt_pk_bf16_f32 v170, v23, v39
	v_cvt_pk_bf16_f32 v171, v55, v71
	ds_write2_b32 v15, v170, v171 offset0:204 offset1:236
	v_fmac_f32_e32 v24, v120, v23
	v_fmac_f32_e32 v40, v120, v39
	v_fmac_f32_e32 v56, v122, v55
	v_fmac_f32_e32 v72, v122, v71
	v_fmac_f32_e32 v24, v124, v39
	v_fmac_f32_e32 v40, v121, v23
	v_fmac_f32_e32 v56, v125, v71
	v_fmac_f32_e32 v72, v123, v55
	v_cvt_pk_bf16_f32 v170, v24, v40
	v_cvt_pk_bf16_f32 v171, v56, v72
	ds_write2_b32 v184, v170, v171 offset1:32
	v_fmac_f32_e32 v25, v120, v24
	v_fmac_f32_e32 v41, v120, v40
	v_fmac_f32_e32 v57, v122, v56
	v_fmac_f32_e32 v73, v122, v72
	v_fmac_f32_e32 v25, v124, v40
	v_fmac_f32_e32 v41, v121, v24
	v_fmac_f32_e32 v57, v125, v72
	v_fmac_f32_e32 v73, v123, v56
	v_cvt_pk_bf16_f32 v170, v25, v41
	v_cvt_pk_bf16_f32 v171, v57, v73
	ds_write2_b32 v184, v170, v171 offset0:68 offset1:100
	v_fmac_f32_e32 v26, v120, v25
	v_fmac_f32_e32 v42, v120, v41
	v_fmac_f32_e32 v58, v122, v57
	v_fmac_f32_e32 v74, v122, v73
	v_fmac_f32_e32 v26, v124, v41
	v_fmac_f32_e32 v42, v121, v25
	v_fmac_f32_e32 v58, v125, v73
	v_fmac_f32_e32 v74, v123, v57
	v_cvt_pk_bf16_f32 v170, v26, v42
	v_cvt_pk_bf16_f32 v171, v58, v74
	ds_write2_b32 v184, v170, v171 offset0:136 offset1:168
	v_fmac_f32_e32 v27, v120, v26
	v_fmac_f32_e32 v43, v120, v42
	v_fmac_f32_e32 v59, v122, v58
	v_fmac_f32_e32 v75, v122, v74
	v_fmac_f32_e32 v27, v124, v42
	v_fmac_f32_e32 v43, v121, v26
	v_fmac_f32_e32 v59, v125, v74
	v_fmac_f32_e32 v75, v123, v58
	v_cvt_pk_bf16_f32 v170, v27, v43
	v_cvt_pk_bf16_f32 v171, v59, v75
	ds_write2_b32 v184, v170, v171 offset0:204 offset1:236
	v_fmac_f32_e32 v28, v120, v27
	v_fmac_f32_e32 v44, v120, v43
	v_fmac_f32_e32 v60, v122, v59
	v_fmac_f32_e32 v76, v122, v75
	v_fmac_f32_e32 v28, v124, v43
	v_fmac_f32_e32 v44, v121, v27
	v_fmac_f32_e32 v60, v125, v75
	v_fmac_f32_e32 v76, v123, v59
	v_cvt_pk_bf16_f32 v170, v28, v44
	v_cvt_pk_bf16_f32 v171, v60, v76
	ds_write2_b32 v185, v170, v171 offset1:32
	v_fmac_f32_e32 v29, v120, v28
	v_fmac_f32_e32 v45, v120, v44
	v_fmac_f32_e32 v61, v122, v60
	v_fmac_f32_e32 v77, v122, v76
	v_fmac_f32_e32 v29, v124, v44
	v_fmac_f32_e32 v45, v121, v28
	v_fmac_f32_e32 v61, v125, v76
	v_fmac_f32_e32 v77, v123, v60
	v_cvt_pk_bf16_f32 v170, v29, v45
	v_cvt_pk_bf16_f32 v171, v61, v77
	ds_write2_b32 v185, v170, v171 offset0:68 offset1:100
	v_fmac_f32_e32 v30, v120, v29
	v_fmac_f32_e32 v46, v120, v45
	v_fmac_f32_e32 v62, v122, v61
	v_fmac_f32_e32 v78, v122, v77
	v_fmac_f32_e32 v30, v124, v45
	v_fmac_f32_e32 v46, v121, v29
	v_fmac_f32_e32 v62, v125, v77
	v_fmac_f32_e32 v78, v123, v61
	v_cvt_pk_bf16_f32 v170, v30, v46
	v_cvt_pk_bf16_f32 v171, v62, v78
	ds_write2_b32 v185, v170, v171 offset0:136 offset1:168
	v_fmac_f32_e32 v31, v120, v30
	v_fmac_f32_e32 v47, v120, v46
	v_fmac_f32_e32 v63, v122, v62
	v_fmac_f32_e32 v79, v122, v78
	v_fmac_f32_e32 v31, v124, v46
	v_fmac_f32_e32 v47, v121, v30
	v_fmac_f32_e32 v63, v125, v78
	v_fmac_f32_e32 v79, v123, v62
	v_cvt_pk_bf16_f32 v170, v31, v47
	v_cvt_pk_bf16_f32 v171, v63, v79
	ds_write2_b32 v185, v170, v171 offset0:204 offset1:236
	v_mov_b32_e32 v126, v31
	v_mov_b32_e32 v127, v47
	v_mov_b32_e32 v128, v63
	v_mov_b32_e32 v129, v79
	s_add_u32 s14, s14, 2
	s_cmp_lt_u32 s14, 16
	s_cbranch_scc1 .Lssm_tile_d0m1
	ds_read_b128 v[130:133], v187
	ds_read_b128 v[134:137], v187 offset:64
	ds_read_b128 v[138:141], v187 offset:128
	ds_read_b128 v[142:145], v187 offset:192
	ds_read_b128 v[146:149], v187 offset:4352
	ds_read_b128 v[150:153], v187 offset:4416
	ds_read_b128 v[154:157], v187 offset:4480
	ds_read_b128 v[158:161], v187 offset:4544
	s_waitcnt vmcnt(0) lgkmcnt(0)
	v_mfma_f32_16x16x32_bf16 v[162:165], v[104:107], v[130:133], 0
	v_mfma_f32_16x16x32_bf16 v[166:169], v[104:107], v[146:149], 0
	v_mfma_f32_16x16x32_bf16 v[162:165], v[108:111], v[134:137], v[162:165]
	v_mfma_f32_16x16x32_bf16 v[166:169], v[108:111], v[150:153], v[166:169]
	v_mfma_f32_16x16x32_bf16 v[162:165], v[112:115], v[138:141], v[162:165]
	v_mfma_f32_16x16x32_bf16 v[166:169], v[112:115], v[154:157], v[166:169]
	v_mfma_f32_16x16x32_bf16 v[162:165], v[116:119], v[142:145], v[162:165]
	v_mfma_f32_16x16x32_bf16 v[166:169], v[116:119], v[158:161], v[166:169]
	s_nop 7
	v_cvt_pk_bf16_f32 v6, v162, v163
	v_cvt_pk_bf16_f32 v7, v164, v165
	ds_write_b64 v193, v[6:7]
	v_cvt_pk_bf16_f32 v6, v166, v167
	v_cvt_pk_bf16_f32 v7, v168, v169
	ds_write_b64 v194, v[6:7]
	s_add_u32 s30, s30, 0x8000000
	s_add_u32 s16, s60, s30
	s_addc_u32 s17, s61, 0
	s_add_u32 s18, s16, 0x4000
	s_addc_u32 s19, s17, 0
	global_store_dword v196, v126, s[16:17]
	global_store_dword v196, v128, s[16:17] offset:128
	global_store_dword v196, v127, s[18:19]
	global_store_dword v196, v129, s[18:19] offset:128
	s_waitcnt vmcnt(0) lgkmcnt(0)
	v_and_b32_e32 v6, 31, v191
	v_lshrrev_b32_e32 v7, 5, v191
	v_and_b32_e32 v8, 15, v191
	v_lshrrev_b32_e32 v9, 4, v191
	v_lshrrev_b32_e32 v10, 3, v6
	v_lshlrev_b32_e32 v10, 10, v10
	v_and_b32_e32 v11, 7, v6
	v_lshl_add_u32 v10, v11, 5, v10
	v_lshl_add_u32 v10, v7, 8, v10
	s_add_u32 s28, s24, 64
	s_lshl_b32 s29, s28, 13
	s_add_u32 s29, s29, 0x200000
	s_add_u32 s10, s62, s29
	s_addc_u32 s11, s63, 0
	s_add_u32 s12, s10, 0x1000
	s_addc_u32 s13, s11, 0
	global_load_dwordx4 v[88:91], v10, s[10:11]
	global_load_dwordx4 v[92:95], v10, s[10:11] offset:16
	global_load_dwordx4 v[96:99], v10, s[12:13]
	global_load_dwordx4 v[100:103], v10, s[12:13] offset:16
	s_lshl_b32 s29, s28, 12
	s_add_u32 s29, s29, 0x300000
	s_add_u32 s16, s62, s29
	s_addc_u32 s17, s63, 0
	v_lshlrev_b32_e32 v10, 4, v191
	global_load_dwordx4 v[104:107], v10, s[16:17]
	global_load_dwordx4 v[108:111], v10, s[16:17] offset:1024
	global_load_dwordx4 v[112:115], v10, s[16:17] offset:2048
	global_load_dwordx4 v[116:119], v10, s[16:17] offset:3072
	s_lshl_b32 s29, s28, 9
	s_add_u32 s29, s29, 0x100000
	s_add_u32 s18, s62, s29
	s_addc_u32 s19, s63, 0
	v_lshlrev_b32_e32 v10, 3, v6
	global_load_dwordx2 v[120:121], v10, s[18:19]
	global_load_dwordx2 v[122:123], v10, s[18:19] offset:256
	s_lshl_b32 s30, s23, 1
	s_add_u32 s30, s30, 1
	s_lshl_b32 s30, s30, 15
	s_lshl_b32 s31, s24, 8
	s_add_u32 s30, s30, s31
	v_lshlrev_b32_e32 v10, 16, v7
	v_lshl_add_u32 v10, v6, 2, v10
	v_mov_b32_e32 v196, v10
	v_mov_b32_e32 v126, 0
	v_mov_b32_e32 v127, 0
	v_mov_b32_e32 v128, 0
	v_mov_b32_e32 v129, 0
	v_readlane_b32 s34, v254, 28
	v_readlane_b32 s35, v254, 29
	s_nop 3
	s_lshl_b32 s31, s24, 6
	s_add_u32 s34, s34, s31
	s_addc_u32 s35, s35, 0
	v_lshlrev_b32_e32 v10, 4, v9
	global_load_dwordx4 v[176:179], v10, s[34:35]
	s_mul_i32 s31, s25, 0x1800
	s_lshl_b32 s29, s24, 5
	s_add_u32 s31, s31, s29
	s_add_u32 s31, s31, 0x8801000
	s_add_u32 s4, s62, s31
	s_addc_u32 s5, s63, 0
	v_lshrrev_b32_e32 v10, 3, v6
	v_and_b32_e32 v11, 3, v6
	v_lshl_add_u32 v10, v10, 2, v11
	v_mul_u32_u24_e32 v10, 0x1800, v10
	v_lshl_add_u32 v10, v7, 4, v10
	v_bfe_u32 v11, v6, 2, 1
	v_mul_u32_u24_e32 v11, 1572864, v11
	v_add_u32_e32 v186, v10, v11
	v_mul_u32_u24_e32 v10, 0x1100, v7
	v_lshl_add_u32 v10, v6, 2, v10
	v_add_u32_e32 v14, s20, v10
	v_add_u32_e32 v15, 1088, v14
	v_add_u32_e32 v184, 2176, v14
	v_add_u32_e32 v185, 3264, v14
	v_mul_u32_u24_e32 v10, 0x110, v8
	v_lshl_add_u32 v10, v9, 4, v10
	v_add_u32_e32 v187, s20, v10
	v_lshlrev_b32_e32 v10, 5, v8
	v_lshl_add_u32 v10, v9, 3, v10
	v_add_u32_e32 v188, s21, v10
	v_add_u32_e32 v189, 0x2000, v188
	v_lshlrev_b32_e32 v10, 11, v8
	v_lshl_add_u32 v193, v9, 3, v10
	v_add_u32_e32 v194, 0x80000, v193
	v_mul_u32_u24_e32 v10, 0x1800, v8
	v_lshl_add_u32 v195, v9, 3, v10
	s_lshl_b32 s31, s25, 11
	s_lshl_b32 s29, s24, 5
	s_add_u32 s31, s31, s29
	s_add_u32 s31, s31, 0x14800000
	s_add_u32 s6, s62, s31
	s_addc_u32 s7, s63, 0
	v_mov_b32_e32 v1, 0x3dd2d3e8
	s_add_u32 s34, s4, 1474560
	s_addc_u32 s35, s5, 0
	global_load_dwordx4 v[80:83], v186, s[34:35]
	s_add_u32 s42, s34, 1572864
	s_addc_u32 s43, s35, 0
	global_load_dwordx2 v[180:181], v195, s[34:35]
	global_load_dwordx2 v[182:183], v195, s[42:43]
	s_mov_b64 s[10:11], s[34:35]
	s_sub_u32 s10, s10, 98304
	s_subb_u32 s11, s11, 0
	global_load_dwordx4 v[84:87], v186, s[10:11]
	s_mov_b64 s[34:35], s[10:11]
	s_add_u32 s42, s34, 1572864
	s_addc_u32 s43, s35, 0
	s_sub_u32 s10, s10, 98304
	s_subb_u32 s11, s11, 0
	s_add_u32 s12, s6, 491520
	s_addc_u32 s13, s7, 0
	s_mov_b32 s36, 7680
	s_mov_b32 s14, 0
	s_waitcnt vmcnt(0)
	v_xor_b32_e32 v124, 0x80000000, v121
	v_xor_b32_e32 v125, 0x80000000, v123
	v_add_u32_e32 v12, s36, v188
	v_add_u32_e32 v13, s36, v189
.Lssm_tile_d1m2:
	s_cmp_eq_u32 s14, 0
	s_cbranch_scc1 .Lssm_sk1_d1m2
	ds_read_b128 v[130:133], v187
	ds_read_b128 v[134:137], v187 offset:64
	ds_read_b128 v[138:141], v187 offset:128
	ds_read_b128 v[142:145], v187 offset:192
	ds_read_b128 v[146:149], v187 offset:4352
	ds_read_b128 v[150:153], v187 offset:4416
	ds_read_b128 v[154:157], v187 offset:4480
	ds_read_b128 v[158:161], v187 offset:4544
	ds_read_b64 v[172:173], v12
	ds_read_b64 v[174:175], v13
.Lssm_sk1_d1m2:
	s_waitcnt vmcnt(5)
	v_mfma_f32_32x32x16_bf16 v[16:31], v[80:83], v[88:91], 0
	v_mfma_f32_32x32x16_bf16 v[32:47], v[80:83], v[92:95], 0
	v_mfma_f32_32x32x16_bf16 v[48:63], v[80:83], v[96:99], 0
	v_mfma_f32_32x32x16_bf16 v[64:79], v[80:83], v[100:103], 0
	s_cmp_eq_u32 s14, 0
	s_cbranch_scc1 .Lssm_sk3_d1m2
	s_waitcnt lgkmcnt(0)
	v_mfma_f32_16x16x32_bf16 v[162:165], v[104:107], v[130:133], 0
	v_mfma_f32_16x16x32_bf16 v[166:169], v[104:107], v[146:149], 0
	v_mfma_f32_16x16x32_bf16 v[162:165], v[108:111], v[134:137], v[162:165]
	v_mfma_f32_16x16x32_bf16 v[166:169], v[108:111], v[150:153], v[166:169]
	v_mfma_f32_16x16x32_bf16 v[162:165], v[112:115], v[138:141], v[162:165]
	v_mfma_f32_16x16x32_bf16 v[166:169], v[112:115], v[154:157], v[166:169]
	v_mfma_f32_16x16x32_bf16 v[162:165], v[116:119], v[142:145], v[162:165]
	v_mfma_f32_16x16x32_bf16 v[166:169], v[116:119], v[158:161], v[166:169]
	s_nop 7
	v_lshlrev_b32_e32 v6, 16, v172
	v_and_b32_e32 v7, 0xffff0000, v172
	v_lshlrev_b32_e32 v8, 16, v173
	v_and_b32_e32 v9, 0xffff0000, v173
	v_lshlrev_b32_e32 v10, 16, v2
	v_and_b32_e32 v11, 0xffff0000, v2
	v_lshlrev_b32_e32 v170, 16, v3
	v_and_b32_e32 v171, 0xffff0000, v3
	v_add_f32_e32 v6, v6, v162
	v_add_f32_e32 v7, v7, v163
	v_add_f32_e32 v8, v8, v164
	v_add_f32_e32 v9, v9, v165
	v_fmac_f32_e32 v6, v176, v10
	v_fmac_f32_e32 v7, v177, v11
	v_fmac_f32_e32 v8, v178, v170
	v_fmac_f32_e32 v9, v179, v171
	v_mul_f32_e32 v10, v6, v6
	v_mul_f32_e32 v11, v7, v7
	v_mul_f32_e32 v170, v8, v8
	v_mul_f32_e32 v171, v9, v9
	v_fmaak_f32 v10, v1, v10, 0x40135761
	v_fmaak_f32 v11, v1, v11, 0x40135761
	v_fmaak_f32 v170, v1, v170, 0x40135761
	v_fmaak_f32 v171, v1, v171, 0x40135761
	v_mul_f32_e32 v10, v6, v10
	v_mul_f32_e32 v11, v7, v11
	v_mul_f32_e32 v170, v8, v170
	v_mul_f32_e32 v171, v9, v171
	v_exp_f32_e64 v10, -v10
	v_exp_f32_e64 v11, -v11
	v_exp_f32_e64 v170, -v170
	v_exp_f32_e64 v171, -v171
	v_add_f32_e32 v10, 1.0, v10
	v_add_f32_e32 v11, 1.0, v11
	v_add_f32_e32 v170, 1.0, v170
	v_add_f32_e32 v171, 1.0, v171
	v_rcp_f32_e32 v10, v10
	v_rcp_f32_e32 v11, v11
	v_rcp_f32_e32 v170, v170
	v_rcp_f32_e32 v171, v171
	v_mul_f32_e32 v6, v6, v10
	v_mul_f32_e32 v7, v7, v11
	v_mul_f32_e32 v8, v8, v170
	v_mul_f32_e32 v9, v9, v171
	v_cvt_pk_bf16_f32 v10, v6, v7
	v_cvt_pk_bf16_f32 v11, v8, v9
	global_store_dwordx2 v193, v[10:11], s[12:13]
	v_lshlrev_b32_e32 v6, 16, v174
	v_and_b32_e32 v7, 0xffff0000, v174
	v_lshlrev_b32_e32 v8, 16, v175
	v_and_b32_e32 v9, 0xffff0000, v175
	v_lshlrev_b32_e32 v10, 16, v4
	v_and_b32_e32 v11, 0xffff0000, v4
	v_lshlrev_b32_e32 v170, 16, v5
	v_and_b32_e32 v171, 0xffff0000, v5
	v_add_f32_e32 v6, v6, v166
	v_add_f32_e32 v7, v7, v167
	v_add_f32_e32 v8, v8, v168
	v_add_f32_e32 v9, v9, v169
	v_fmac_f32_e32 v6, v176, v10
	v_fmac_f32_e32 v7, v177, v11
	v_fmac_f32_e32 v8, v178, v170
	v_fmac_f32_e32 v9, v179, v171
	v_mul_f32_e32 v10, v6, v6
	v_mul_f32_e32 v11, v7, v7
	v_mul_f32_e32 v170, v8, v8
	v_mul_f32_e32 v171, v9, v9
	v_fmaak_f32 v10, v1, v10, 0x40135761
	v_fmaak_f32 v11, v1, v11, 0x40135761
	v_fmaak_f32 v170, v1, v170, 0x40135761
	v_fmaak_f32 v171, v1, v171, 0x40135761
	v_mul_f32_e32 v10, v6, v10
	v_mul_f32_e32 v11, v7, v11
	v_mul_f32_e32 v170, v8, v170
	v_mul_f32_e32 v171, v9, v171
	v_exp_f32_e64 v10, -v10
	v_exp_f32_e64 v11, -v11
	v_exp_f32_e64 v170, -v170
	v_exp_f32_e64 v171, -v171
	v_add_f32_e32 v10, 1.0, v10
	v_add_f32_e32 v11, 1.0, v11
	v_add_f32_e32 v170, 1.0, v170
	v_add_f32_e32 v171, 1.0, v171
	v_rcp_f32_e32 v10, v10
	v_rcp_f32_e32 v11, v11
	v_rcp_f32_e32 v170, v170
	v_rcp_f32_e32 v171, v171
	v_mul_f32_e32 v6, v6, v10
	v_mul_f32_e32 v7, v7, v11
	v_mul_f32_e32 v8, v8, v170
	v_mul_f32_e32 v9, v9, v171
	v_cvt_pk_bf16_f32 v10, v6, v7
	v_cvt_pk_bf16_f32 v11, v8, v9
	global_store_dwordx2 v194, v[10:11], s[12:13]
	s_sub_u32 s12, s12, 32768
	s_subb_u32 s13, s13, 0
	s_sub_u32 s36, s36, 512
	v_add_u32_e32 v12, s36, v188
	v_add_u32_e32 v13, s36, v189
.Lssm_sk3_d1m2:
	s_nop 9
	global_load_dwordx2 v[2:3], v195, s[34:35]
	global_load_dwordx2 v[4:5], v195, s[42:43]
	s_sub_u32 s42, s42, 98304
	s_subb_u32 s43, s43, 0
	global_load_dwordx4 v[80:83], v186, s[10:11]
	s_sub_u32 s34, s34, 98304
	s_subb_u32 s35, s35, 0
	s_sub_u32 s10, s10, 98304
	s_subb_u32 s11, s11, 0
	v_fmac_f32_e32 v31, v120, v126
	v_fmac_f32_e32 v47, v120, v127
	v_fmac_f32_e32 v63, v122, v128
	v_fmac_f32_e32 v79, v122, v129
	v_fmac_f32_e32 v31, v124, v127
	v_fmac_f32_e32 v47, v121, v126
	v_fmac_f32_e32 v63, v125, v129
	v_fmac_f32_e32 v79, v123, v128
	v_cvt_pk_bf16_f32 v170, v31, v47
	v_cvt_pk_bf16_f32 v171, v63, v79
	ds_write2_b32 v185, v170, v171 offset0:204 offset1:236
	v_fmac_f32_e32 v30, v120, v31
	v_fmac_f32_e32 v46, v120, v47
	v_fmac_f32_e32 v62, v122, v63
	v_fmac_f32_e32 v78, v122, v79
	v_fmac_f32_e32 v30, v124, v47
	v_fmac_f32_e32 v46, v121, v31
	v_fmac_f32_e32 v62, v125, v79
	v_fmac_f32_e32 v78, v123, v63
	v_cvt_pk_bf16_f32 v170, v30, v46
	v_cvt_pk_bf16_f32 v171, v62, v78
	ds_write2_b32 v185, v170, v171 offset0:136 offset1:168
	v_fmac_f32_e32 v29, v120, v30
	v_fmac_f32_e32 v45, v120, v46
	v_fmac_f32_e32 v61, v122, v62
	v_fmac_f32_e32 v77, v122, v78
	v_fmac_f32_e32 v29, v124, v46
	v_fmac_f32_e32 v45, v121, v30
	v_fmac_f32_e32 v61, v125, v78
	v_fmac_f32_e32 v77, v123, v62
	v_cvt_pk_bf16_f32 v170, v29, v45
	v_cvt_pk_bf16_f32 v171, v61, v77
	ds_write2_b32 v185, v170, v171 offset0:68 offset1:100
	v_fmac_f32_e32 v28, v120, v29
	v_fmac_f32_e32 v44, v120, v45
	v_fmac_f32_e32 v60, v122, v61
	v_fmac_f32_e32 v76, v122, v77
	v_fmac_f32_e32 v28, v124, v45
	v_fmac_f32_e32 v44, v121, v29
	v_fmac_f32_e32 v60, v125, v77
	v_fmac_f32_e32 v76, v123, v61
	v_cvt_pk_bf16_f32 v170, v28, v44
	v_cvt_pk_bf16_f32 v171, v60, v76
	ds_write2_b32 v185, v170, v171 offset1:32
	v_fmac_f32_e32 v27, v120, v28
	v_fmac_f32_e32 v43, v120, v44
	v_fmac_f32_e32 v59, v122, v60
	v_fmac_f32_e32 v75, v122, v76
	v_fmac_f32_e32 v27, v124, v44
	v_fmac_f32_e32 v43, v121, v28
	v_fmac_f32_e32 v59, v125, v76
	v_fmac_f32_e32 v75, v123, v60
	v_cvt_pk_bf16_f32 v170, v27, v43
	v_cvt_pk_bf16_f32 v171, v59, v75
	ds_write2_b32 v184, v170, v171 offset0:204 offset1:236
	v_fmac_f32_e32 v26, v120, v27
	v_fmac_f32_e32 v42, v120, v43
	v_fmac_f32_e32 v58, v122, v59
	v_fmac_f32_e32 v74, v122, v75
	v_fmac_f32_e32 v26, v124, v43
	v_fmac_f32_e32 v42, v121, v27
	v_fmac_f32_e32 v58, v125, v75
	v_fmac_f32_e32 v74, v123, v59
	v_cvt_pk_bf16_f32 v170, v26, v42
	v_cvt_pk_bf16_f32 v171, v58, v74
	ds_write2_b32 v184, v170, v171 offset0:136 offset1:168
	v_fmac_f32_e32 v25, v120, v26
	v_fmac_f32_e32 v41, v120, v42
	v_fmac_f32_e32 v57, v122, v58
	v_fmac_f32_e32 v73, v122, v74
	v_fmac_f32_e32 v25, v124, v42
	v_fmac_f32_e32 v41, v121, v26
	v_fmac_f32_e32 v57, v125, v74
	v_fmac_f32_e32 v73, v123, v58
	v_cvt_pk_bf16_f32 v170, v25, v41
	v_cvt_pk_bf16_f32 v171, v57, v73
	ds_write2_b32 v184, v170, v171 offset0:68 offset1:100
	v_fmac_f32_e32 v24, v120, v25
	v_fmac_f32_e32 v40, v120, v41
	v_fmac_f32_e32 v56, v122, v57
	v_fmac_f32_e32 v72, v122, v73
	v_fmac_f32_e32 v24, v124, v41
	v_fmac_f32_e32 v40, v121, v25
	v_fmac_f32_e32 v56, v125, v73
	v_fmac_f32_e32 v72, v123, v57
	v_cvt_pk_bf16_f32 v170, v24, v40
	v_cvt_pk_bf16_f32 v171, v56, v72
	ds_write2_b32 v184, v170, v171 offset1:32
	v_fmac_f32_e32 v23, v120, v24
	v_fmac_f32_e32 v39, v120, v40
	v_fmac_f32_e32 v55, v122, v56
	v_fmac_f32_e32 v71, v122, v72
	v_fmac_f32_e32 v23, v124, v40
	v_fmac_f32_e32 v39, v121, v24
	v_fmac_f32_e32 v55, v125, v72
	v_fmac_f32_e32 v71, v123, v56
	v_cvt_pk_bf16_f32 v170, v23, v39
	v_cvt_pk_bf16_f32 v171, v55, v71
	ds_write2_b32 v15, v170, v171 offset0:204 offset1:236
	v_fmac_f32_e32 v22, v120, v23
	v_fmac_f32_e32 v38, v120, v39
	v_fmac_f32_e32 v54, v122, v55
	v_fmac_f32_e32 v70, v122, v71
	v_fmac_f32_e32 v22, v124, v39
	v_fmac_f32_e32 v38, v121, v23
	v_fmac_f32_e32 v54, v125, v71
	v_fmac_f32_e32 v70, v123, v55
	v_cvt_pk_bf16_f32 v170, v22, v38
	v_cvt_pk_bf16_f32 v171, v54, v70
	ds_write2_b32 v15, v170, v171 offset0:136 offset1:168
	v_fmac_f32_e32 v21, v120, v22
	v_fmac_f32_e32 v37, v120, v38
	v_fmac_f32_e32 v53, v122, v54
	v_fmac_f32_e32 v69, v122, v70
	v_fmac_f32_e32 v21, v124, v38
	v_fmac_f32_e32 v37, v121, v22
	v_fmac_f32_e32 v53, v125, v70
	v_fmac_f32_e32 v69, v123, v54
	v_cvt_pk_bf16_f32 v170, v21, v37
	v_cvt_pk_bf16_f32 v171, v53, v69
	ds_write2_b32 v15, v170, v171 offset0:68 offset1:100
	v_fmac_f32_e32 v20, v120, v21
	v_fmac_f32_e32 v36, v120, v37
	v_fmac_f32_e32 v52, v122, v53
	v_fmac_f32_e32 v68, v122, v69
	v_fmac_f32_e32 v20, v124, v37
	v_fmac_f32_e32 v36, v121, v21
	v_fmac_f32_e32 v52, v125, v69
	v_fmac_f32_e32 v68, v123, v53
	v_cvt_pk_bf16_f32 v170, v20, v36
	v_cvt_pk_bf16_f32 v171, v52, v68
	ds_write2_b32 v15, v170, v171 offset1:32
	v_fmac_f32_e32 v19, v120, v20
	v_fmac_f32_e32 v35, v120, v36
	v_fmac_f32_e32 v51, v122, v52
	v_fmac_f32_e32 v67, v122, v68
	v_fmac_f32_e32 v19, v124, v36
	v_fmac_f32_e32 v35, v121, v20
	v_fmac_f32_e32 v51, v125, v68
	v_fmac_f32_e32 v67, v123, v52
	v_cvt_pk_bf16_f32 v170, v19, v35
	v_cvt_pk_bf16_f32 v171, v51, v67
	ds_write2_b32 v14, v170, v171 offset0:204 offset1:236
	v_fmac_f32_e32 v18, v120, v19
	v_fmac_f32_e32 v34, v120, v35
	v_fmac_f32_e32 v50, v122, v51
	v_fmac_f32_e32 v66, v122, v67
	v_fmac_f32_e32 v18, v124, v35
	v_fmac_f32_e32 v34, v121, v19
	v_fmac_f32_e32 v50, v125, v67
	v_fmac_f32_e32 v66, v123, v51
	v_cvt_pk_bf16_f32 v170, v18, v34
	v_cvt_pk_bf16_f32 v171, v50, v66
	ds_write2_b32 v14, v170, v171 offset0:136 offset1:168
	v_fmac_f32_e32 v17, v120, v18
	v_fmac_f32_e32 v33, v120, v34
	v_fmac_f32_e32 v49, v122, v50
	v_fmac_f32_e32 v65, v122, v66
	v_fmac_f32_e32 v17, v124, v34
	v_fmac_f32_e32 v33, v121, v18
	v_fmac_f32_e32 v49, v125, v66
	v_fmac_f32_e32 v65, v123, v50
	v_cvt_pk_bf16_f32 v170, v17, v33
	v_cvt_pk_bf16_f32 v171, v49, v65
	ds_write2_b32 v14, v170, v171 offset0:68 offset1:100
	v_fmac_f32_e32 v16, v120, v17
	v_fmac_f32_e32 v32, v120, v33
	v_fmac_f32_e32 v48, v122, v49
	v_fmac_f32_e32 v64, v122, v65
	v_fmac_f32_e32 v16, v124, v33
	v_fmac_f32_e32 v32, v121, v17
	v_fmac_f32_e32 v48, v125, v65
	v_fmac_f32_e32 v64, v123, v49
	v_cvt_pk_bf16_f32 v170, v16, v32
	v_cvt_pk_bf16_f32 v171, v48, v64
	ds_write2_b32 v14, v170, v171 offset1:32
	v_mov_b32_e32 v126, v16
	v_mov_b32_e32 v127, v32
	v_mov_b32_e32 v128, v48
	v_mov_b32_e32 v129, v64
	ds_read_b128 v[130:133], v187
	ds_read_b128 v[134:137], v187 offset:64
	ds_read_b128 v[138:141], v187 offset:128
	ds_read_b128 v[142:145], v187 offset:192
	ds_read_b128 v[146:149], v187 offset:4352
	ds_read_b128 v[150:153], v187 offset:4416
	ds_read_b128 v[154:157], v187 offset:4480
	ds_read_b128 v[158:161], v187 offset:4544
	ds_read_b64 v[172:173], v12
	ds_read_b64 v[174:175], v13
	s_waitcnt vmcnt(5)
	v_mfma_f32_32x32x16_bf16 v[16:31], v[84:87], v[88:91], 0
	v_mfma_f32_32x32x16_bf16 v[32:47], v[84:87], v[92:95], 0
	v_mfma_f32_32x32x16_bf16 v[48:63], v[84:87], v[96:99], 0
	v_mfma_f32_32x32x16_bf16 v[64:79], v[84:87], v[100:103], 0
	s_waitcnt lgkmcnt(0)
	v_mfma_f32_16x16x32_bf16 v[162:165], v[104:107], v[130:133], 0
	v_mfma_f32_16x16x32_bf16 v[166:169], v[104:107], v[146:149], 0
	v_mfma_f32_16x16x32_bf16 v[162:165], v[108:111], v[134:137], v[162:165]
	v_mfma_f32_16x16x32_bf16 v[166:169], v[108:111], v[150:153], v[166:169]
	v_mfma_f32_16x16x32_bf16 v[162:165], v[112:115], v[138:141], v[162:165]
	v_mfma_f32_16x16x32_bf16 v[166:169], v[112:115], v[154:157], v[166:169]
	v_mfma_f32_16x16x32_bf16 v[162:165], v[116:119], v[142:145], v[162:165]
	v_mfma_f32_16x16x32_bf16 v[166:169], v[116:119], v[158:161], v[166:169]
	s_nop 7
	v_lshlrev_b32_e32 v6, 16, v172
	v_and_b32_e32 v7, 0xffff0000, v172
	v_lshlrev_b32_e32 v8, 16, v173
	v_and_b32_e32 v9, 0xffff0000, v173
	v_lshlrev_b32_e32 v10, 16, v180
	v_and_b32_e32 v11, 0xffff0000, v180
	v_lshlrev_b32_e32 v170, 16, v181
	v_and_b32_e32 v171, 0xffff0000, v181
	v_add_f32_e32 v6, v6, v162
	v_add_f32_e32 v7, v7, v163
	v_add_f32_e32 v8, v8, v164
	v_add_f32_e32 v9, v9, v165
	v_fmac_f32_e32 v6, v176, v10
	v_fmac_f32_e32 v7, v177, v11
	v_fmac_f32_e32 v8, v178, v170
	v_fmac_f32_e32 v9, v179, v171
	v_mul_f32_e32 v10, v6, v6
	v_mul_f32_e32 v11, v7, v7
	v_mul_f32_e32 v170, v8, v8
	v_mul_f32_e32 v171, v9, v9
	v_fmaak_f32 v10, v1, v10, 0x40135761
	v_fmaak_f32 v11, v1, v11, 0x40135761
	v_fmaak_f32 v170, v1, v170, 0x40135761
	v_fmaak_f32 v171, v1, v171, 0x40135761
	v_mul_f32_e32 v10, v6, v10
	v_mul_f32_e32 v11, v7, v11
	v_mul_f32_e32 v170, v8, v170
	v_mul_f32_e32 v171, v9, v171
	v_exp_f32_e64 v10, -v10
	v_exp_f32_e64 v11, -v11
	v_exp_f32_e64 v170, -v170
	v_exp_f32_e64 v171, -v171
	v_add_f32_e32 v10, 1.0, v10
	v_add_f32_e32 v11, 1.0, v11
	v_add_f32_e32 v170, 1.0, v170
	v_add_f32_e32 v171, 1.0, v171
	v_rcp_f32_e32 v10, v10
	v_rcp_f32_e32 v11, v11
	v_rcp_f32_e32 v170, v170
	v_rcp_f32_e32 v171, v171
	v_mul_f32_e32 v6, v6, v10
	v_mul_f32_e32 v7, v7, v11
	v_mul_f32_e32 v8, v8, v170
	v_mul_f32_e32 v9, v9, v171
	v_cvt_pk_bf16_f32 v10, v6, v7
	v_cvt_pk_bf16_f32 v11, v8, v9
	global_store_dwordx2 v193, v[10:11], s[12:13]
	v_lshlrev_b32_e32 v6, 16, v174
	v_and_b32_e32 v7, 0xffff0000, v174
	v_lshlrev_b32_e32 v8, 16, v175
	v_and_b32_e32 v9, 0xffff0000, v175
	v_lshlrev_b32_e32 v10, 16, v182
	v_and_b32_e32 v11, 0xffff0000, v182
	v_lshlrev_b32_e32 v170, 16, v183
	v_and_b32_e32 v171, 0xffff0000, v183
	v_add_f32_e32 v6, v6, v166
	v_add_f32_e32 v7, v7, v167
	v_add_f32_e32 v8, v8, v168
	v_add_f32_e32 v9, v9, v169
	v_fmac_f32_e32 v6, v176, v10
	v_fmac_f32_e32 v7, v177, v11
	v_fmac_f32_e32 v8, v178, v170
	v_fmac_f32_e32 v9, v179, v171
	v_mul_f32_e32 v10, v6, v6
	v_mul_f32_e32 v11, v7, v7
	v_mul_f32_e32 v170, v8, v8
	v_mul_f32_e32 v171, v9, v9
	v_fmaak_f32 v10, v1, v10, 0x40135761
	v_fmaak_f32 v11, v1, v11, 0x40135761
	v_fmaak_f32 v170, v1, v170, 0x40135761
	v_fmaak_f32 v171, v1, v171, 0x40135761
	v_mul_f32_e32 v10, v6, v10
	v_mul_f32_e32 v11, v7, v11
	v_mul_f32_e32 v170, v8, v170
	v_mul_f32_e32 v171, v9, v171
	v_exp_f32_e64 v10, -v10
	v_exp_f32_e64 v11, -v11
	v_exp_f32_e64 v170, -v170
	v_exp_f32_e64 v171, -v171
	v_add_f32_e32 v10, 1.0, v10
	v_add_f32_e32 v11, 1.0, v11
	v_add_f32_e32 v170, 1.0, v170
	v_add_f32_e32 v171, 1.0, v171
	v_rcp_f32_e32 v10, v10
	v_rcp_f32_e32 v11, v11
	v_rcp_f32_e32 v170, v170
	v_rcp_f32_e32 v171, v171
	v_mul_f32_e32 v6, v6, v10
	v_mul_f32_e32 v7, v7, v11
	v_mul_f32_e32 v8, v8, v170
	v_mul_f32_e32 v9, v9, v171
	v_cvt_pk_bf16_f32 v10, v6, v7
	v_cvt_pk_bf16_f32 v11, v8, v9
	global_store_dwordx2 v194, v[10:11], s[12:13]
	s_sub_u32 s12, s12, 32768
	s_subb_u32 s13, s13, 0
	s_sub_u32 s36, s36, 512
	v_add_u32_e32 v12, s36, v188
	v_add_u32_e32 v13, s36, v189
	global_load_dwordx2 v[180:181], v195, s[34:35]
	global_load_dwordx2 v[182:183], v195, s[42:43]
	s_sub_u32 s42, s42, 98304
	s_subb_u32 s43, s43, 0
	global_load_dwordx4 v[84:87], v186, s[10:11]
	s_sub_u32 s34, s34, 98304
	s_subb_u32 s35, s35, 0
	s_sub_u32 s10, s10, 98304
	s_subb_u32 s11, s11, 0
	v_fmac_f32_e32 v31, v120, v126
	v_fmac_f32_e32 v47, v120, v127
	v_fmac_f32_e32 v63, v122, v128
	v_fmac_f32_e32 v79, v122, v129
	v_fmac_f32_e32 v31, v124, v127
	v_fmac_f32_e32 v47, v121, v126
	v_fmac_f32_e32 v63, v125, v129
	v_fmac_f32_e32 v79, v123, v128
	v_cvt_pk_bf16_f32 v170, v31, v47
	v_cvt_pk_bf16_f32 v171, v63, v79
	ds_write2_b32 v185, v170, v171 offset0:204 offset1:236
	v_fmac_f32_e32 v30, v120, v31
	v_fmac_f32_e32 v46, v120, v47
	v_fmac_f32_e32 v62, v122, v63
	v_fmac_f32_e32 v78, v122, v79
	v_fmac_f32_e32 v30, v124, v47
	v_fmac_f32_e32 v46, v121, v31
	v_fmac_f32_e32 v62, v125, v79
	v_fmac_f32_e32 v78, v123, v63
	v_cvt_pk_bf16_f32 v170, v30, v46
	v_cvt_pk_bf16_f32 v171, v62, v78
	ds_write2_b32 v185, v170, v171 offset0:136 offset1:168
	v_fmac_f32_e32 v29, v120, v30
	v_fmac_f32_e32 v45, v120, v46
	v_fmac_f32_e32 v61, v122, v62
	v_fmac_f32_e32 v77, v122, v78
	v_fmac_f32_e32 v29, v124, v46
	v_fmac_f32_e32 v45, v121, v30
	v_fmac_f32_e32 v61, v125, v78
	v_fmac_f32_e32 v77, v123, v62
	v_cvt_pk_bf16_f32 v170, v29, v45
	v_cvt_pk_bf16_f32 v171, v61, v77
	ds_write2_b32 v185, v170, v171 offset0:68 offset1:100
	v_fmac_f32_e32 v28, v120, v29
	v_fmac_f32_e32 v44, v120, v45
	v_fmac_f32_e32 v60, v122, v61
	v_fmac_f32_e32 v76, v122, v77
	v_fmac_f32_e32 v28, v124, v45
	v_fmac_f32_e32 v44, v121, v29
	v_fmac_f32_e32 v60, v125, v77
	v_fmac_f32_e32 v76, v123, v61
	v_cvt_pk_bf16_f32 v170, v28, v44
	v_cvt_pk_bf16_f32 v171, v60, v76
	ds_write2_b32 v185, v170, v171 offset1:32
	v_fmac_f32_e32 v27, v120, v28
	v_fmac_f32_e32 v43, v120, v44
	v_fmac_f32_e32 v59, v122, v60
	v_fmac_f32_e32 v75, v122, v76
	v_fmac_f32_e32 v27, v124, v44
	v_fmac_f32_e32 v43, v121, v28
	v_fmac_f32_e32 v59, v125, v76
	v_fmac_f32_e32 v75, v123, v60
	v_cvt_pk_bf16_f32 v170, v27, v43
	v_cvt_pk_bf16_f32 v171, v59, v75
	ds_write2_b32 v184, v170, v171 offset0:204 offset1:236
	v_fmac_f32_e32 v26, v120, v27
	v_fmac_f32_e32 v42, v120, v43
	v_fmac_f32_e32 v58, v122, v59
	v_fmac_f32_e32 v74, v122, v75
	v_fmac_f32_e32 v26, v124, v43
	v_fmac_f32_e32 v42, v121, v27
	v_fmac_f32_e32 v58, v125, v75
	v_fmac_f32_e32 v74, v123, v59
	v_cvt_pk_bf16_f32 v170, v26, v42
	v_cvt_pk_bf16_f32 v171, v58, v74
	ds_write2_b32 v184, v170, v171 offset0:136 offset1:168
	v_fmac_f32_e32 v25, v120, v26
	v_fmac_f32_e32 v41, v120, v42
	v_fmac_f32_e32 v57, v122, v58
	v_fmac_f32_e32 v73, v122, v74
	v_fmac_f32_e32 v25, v124, v42
	v_fmac_f32_e32 v41, v121, v26
	v_fmac_f32_e32 v57, v125, v74
	v_fmac_f32_e32 v73, v123, v58
	v_cvt_pk_bf16_f32 v170, v25, v41
	v_cvt_pk_bf16_f32 v171, v57, v73
	ds_write2_b32 v184, v170, v171 offset0:68 offset1:100
	v_fmac_f32_e32 v24, v120, v25
	v_fmac_f32_e32 v40, v120, v41
	v_fmac_f32_e32 v56, v122, v57
	v_fmac_f32_e32 v72, v122, v73
	v_fmac_f32_e32 v24, v124, v41
	v_fmac_f32_e32 v40, v121, v25
	v_fmac_f32_e32 v56, v125, v73
	v_fmac_f32_e32 v72, v123, v57
	v_cvt_pk_bf16_f32 v170, v24, v40
	v_cvt_pk_bf16_f32 v171, v56, v72
	ds_write2_b32 v184, v170, v171 offset1:32
	v_fmac_f32_e32 v23, v120, v24
	v_fmac_f32_e32 v39, v120, v40
	v_fmac_f32_e32 v55, v122, v56
	v_fmac_f32_e32 v71, v122, v72
	v_fmac_f32_e32 v23, v124, v40
	v_fmac_f32_e32 v39, v121, v24
	v_fmac_f32_e32 v55, v125, v72
	v_fmac_f32_e32 v71, v123, v56
	v_cvt_pk_bf16_f32 v170, v23, v39
	v_cvt_pk_bf16_f32 v171, v55, v71
	ds_write2_b32 v15, v170, v171 offset0:204 offset1:236
	v_fmac_f32_e32 v22, v120, v23
	v_fmac_f32_e32 v38, v120, v39
	v_fmac_f32_e32 v54, v122, v55
	v_fmac_f32_e32 v70, v122, v71
	v_fmac_f32_e32 v22, v124, v39
	v_fmac_f32_e32 v38, v121, v23
	v_fmac_f32_e32 v54, v125, v71
	v_fmac_f32_e32 v70, v123, v55
	v_cvt_pk_bf16_f32 v170, v22, v38
	v_cvt_pk_bf16_f32 v171, v54, v70
	ds_write2_b32 v15, v170, v171 offset0:136 offset1:168
	v_fmac_f32_e32 v21, v120, v22
	v_fmac_f32_e32 v37, v120, v38
	v_fmac_f32_e32 v53, v122, v54
	v_fmac_f32_e32 v69, v122, v70
	v_fmac_f32_e32 v21, v124, v38
	v_fmac_f32_e32 v37, v121, v22
	v_fmac_f32_e32 v53, v125, v70
	v_fmac_f32_e32 v69, v123, v54
	v_cvt_pk_bf16_f32 v170, v21, v37
	v_cvt_pk_bf16_f32 v171, v53, v69
	ds_write2_b32 v15, v170, v171 offset0:68 offset1:100
	v_fmac_f32_e32 v20, v120, v21
	v_fmac_f32_e32 v36, v120, v37
	v_fmac_f32_e32 v52, v122, v53
	v_fmac_f32_e32 v68, v122, v69
	v_fmac_f32_e32 v20, v124, v37
	v_fmac_f32_e32 v36, v121, v21
	v_fmac_f32_e32 v52, v125, v69
	v_fmac_f32_e32 v68, v123, v53
	v_cvt_pk_bf16_f32 v170, v20, v36
	v_cvt_pk_bf16_f32 v171, v52, v68
	ds_write2_b32 v15, v170, v171 offset1:32
	v_fmac_f32_e32 v19, v120, v20
	v_fmac_f32_e32 v35, v120, v36
	v_fmac_f32_e32 v51, v122, v52
	v_fmac_f32_e32 v67, v122, v68
	v_fmac_f32_e32 v19, v124, v36
	v_fmac_f32_e32 v35, v121, v20
	v_fmac_f32_e32 v51, v125, v68
	v_fmac_f32_e32 v67, v123, v52
	v_cvt_pk_bf16_f32 v170, v19, v35
	v_cvt_pk_bf16_f32 v171, v51, v67
	ds_write2_b32 v14, v170, v171 offset0:204 offset1:236
	v_fmac_f32_e32 v18, v120, v19
	v_fmac_f32_e32 v34, v120, v35
	v_fmac_f32_e32 v50, v122, v51
	v_fmac_f32_e32 v66, v122, v67
	v_fmac_f32_e32 v18, v124, v35
	v_fmac_f32_e32 v34, v121, v19
	v_fmac_f32_e32 v50, v125, v67
	v_fmac_f32_e32 v66, v123, v51
	v_cvt_pk_bf16_f32 v170, v18, v34
	v_cvt_pk_bf16_f32 v171, v50, v66
	ds_write2_b32 v14, v170, v171 offset0:136 offset1:168
	v_fmac_f32_e32 v17, v120, v18
	v_fmac_f32_e32 v33, v120, v34
	v_fmac_f32_e32 v49, v122, v50
	v_fmac_f32_e32 v65, v122, v66
	v_fmac_f32_e32 v17, v124, v34
	v_fmac_f32_e32 v33, v121, v18
	v_fmac_f32_e32 v49, v125, v66
	v_fmac_f32_e32 v65, v123, v50
	v_cvt_pk_bf16_f32 v170, v17, v33
	v_cvt_pk_bf16_f32 v171, v49, v65
	ds_write2_b32 v14, v170, v171 offset0:68 offset1:100
	v_fmac_f32_e32 v16, v120, v17
	v_fmac_f32_e32 v32, v120, v33
	v_fmac_f32_e32 v48, v122, v49
	v_fmac_f32_e32 v64, v122, v65
	v_fmac_f32_e32 v16, v124, v33
	v_fmac_f32_e32 v32, v121, v17
	v_fmac_f32_e32 v48, v125, v65
	v_fmac_f32_e32 v64, v123, v49
	v_cvt_pk_bf16_f32 v170, v16, v32
	v_cvt_pk_bf16_f32 v171, v48, v64
	ds_write2_b32 v14, v170, v171 offset1:32
	v_mov_b32_e32 v126, v16
	v_mov_b32_e32 v127, v32
	v_mov_b32_e32 v128, v48
	v_mov_b32_e32 v129, v64
	s_add_u32 s14, s14, 2
	s_cmp_lt_u32 s14, 16
	s_cbranch_scc1 .Lssm_tile_d1m2
	ds_read_b128 v[130:133], v187
	ds_read_b128 v[134:137], v187 offset:64
	ds_read_b128 v[138:141], v187 offset:128
	ds_read_b128 v[142:145], v187 offset:192
	ds_read_b128 v[146:149], v187 offset:4352
	ds_read_b128 v[150:153], v187 offset:4416
	ds_read_b128 v[154:157], v187 offset:4480
	ds_read_b128 v[158:161], v187 offset:4544
	ds_read_b64 v[172:173], v12
	ds_read_b64 v[174:175], v13
	s_waitcnt vmcnt(0) lgkmcnt(0)
	v_mfma_f32_16x16x32_bf16 v[162:165], v[104:107], v[130:133], 0
	v_mfma_f32_16x16x32_bf16 v[166:169], v[104:107], v[146:149], 0
	v_mfma_f32_16x16x32_bf16 v[162:165], v[108:111], v[134:137], v[162:165]
	v_mfma_f32_16x16x32_bf16 v[166:169], v[108:111], v[150:153], v[166:169]
	v_mfma_f32_16x16x32_bf16 v[162:165], v[112:115], v[138:141], v[162:165]
	v_mfma_f32_16x16x32_bf16 v[166:169], v[112:115], v[154:157], v[166:169]
	v_mfma_f32_16x16x32_bf16 v[162:165], v[116:119], v[142:145], v[162:165]
	v_mfma_f32_16x16x32_bf16 v[166:169], v[116:119], v[158:161], v[166:169]
	s_nop 7
	v_lshlrev_b32_e32 v6, 16, v172
	v_and_b32_e32 v7, 0xffff0000, v172
	v_lshlrev_b32_e32 v8, 16, v173
	v_and_b32_e32 v9, 0xffff0000, v173
	v_lshlrev_b32_e32 v10, 16, v2
	v_and_b32_e32 v11, 0xffff0000, v2
	v_lshlrev_b32_e32 v170, 16, v3
	v_and_b32_e32 v171, 0xffff0000, v3
	v_add_f32_e32 v6, v6, v162
	v_add_f32_e32 v7, v7, v163
	v_add_f32_e32 v8, v8, v164
	v_add_f32_e32 v9, v9, v165
	v_fmac_f32_e32 v6, v176, v10
	v_fmac_f32_e32 v7, v177, v11
	v_fmac_f32_e32 v8, v178, v170
	v_fmac_f32_e32 v9, v179, v171
	v_mul_f32_e32 v10, v6, v6
	v_mul_f32_e32 v11, v7, v7
	v_mul_f32_e32 v170, v8, v8
	v_mul_f32_e32 v171, v9, v9
	v_fmaak_f32 v10, v1, v10, 0x40135761
	v_fmaak_f32 v11, v1, v11, 0x40135761
	v_fmaak_f32 v170, v1, v170, 0x40135761
	v_fmaak_f32 v171, v1, v171, 0x40135761
	v_mul_f32_e32 v10, v6, v10
	v_mul_f32_e32 v11, v7, v11
	v_mul_f32_e32 v170, v8, v170
	v_mul_f32_e32 v171, v9, v171
	v_exp_f32_e64 v10, -v10
	v_exp_f32_e64 v11, -v11
	v_exp_f32_e64 v170, -v170
	v_exp_f32_e64 v171, -v171
	v_add_f32_e32 v10, 1.0, v10
	v_add_f32_e32 v11, 1.0, v11
	v_add_f32_e32 v170, 1.0, v170
	v_add_f32_e32 v171, 1.0, v171
	v_rcp_f32_e32 v10, v10
	v_rcp_f32_e32 v11, v11
	v_rcp_f32_e32 v170, v170
	v_rcp_f32_e32 v171, v171
	v_mul_f32_e32 v6, v6, v10
	v_mul_f32_e32 v7, v7, v11
	v_mul_f32_e32 v8, v8, v170
	v_mul_f32_e32 v9, v9, v171
	v_cvt_pk_bf16_f32 v10, v6, v7
	v_cvt_pk_bf16_f32 v11, v8, v9
	global_store_dwordx2 v193, v[10:11], s[12:13]
	v_lshlrev_b32_e32 v6, 16, v174
	v_and_b32_e32 v7, 0xffff0000, v174
	v_lshlrev_b32_e32 v8, 16, v175
	v_and_b32_e32 v9, 0xffff0000, v175
	v_lshlrev_b32_e32 v10, 16, v4
	v_and_b32_e32 v11, 0xffff0000, v4
	v_lshlrev_b32_e32 v170, 16, v5
	v_and_b32_e32 v171, 0xffff0000, v5
	v_add_f32_e32 v6, v6, v166
	v_add_f32_e32 v7, v7, v167
	v_add_f32_e32 v8, v8, v168
	v_add_f32_e32 v9, v9, v169
	v_fmac_f32_e32 v6, v176, v10
	v_fmac_f32_e32 v7, v177, v11
	v_fmac_f32_e32 v8, v178, v170
	v_fmac_f32_e32 v9, v179, v171
	v_mul_f32_e32 v10, v6, v6
	v_mul_f32_e32 v11, v7, v7
	v_mul_f32_e32 v170, v8, v8
	v_mul_f32_e32 v171, v9, v9
	v_fmaak_f32 v10, v1, v10, 0x40135761
	v_fmaak_f32 v11, v1, v11, 0x40135761
	v_fmaak_f32 v170, v1, v170, 0x40135761
	v_fmaak_f32 v171, v1, v171, 0x40135761
	v_mul_f32_e32 v10, v6, v10
	v_mul_f32_e32 v11, v7, v11
	v_mul_f32_e32 v170, v8, v170
	v_mul_f32_e32 v171, v9, v171
	v_exp_f32_e64 v10, -v10
	v_exp_f32_e64 v11, -v11
	v_exp_f32_e64 v170, -v170
	v_exp_f32_e64 v171, -v171
	v_add_f32_e32 v10, 1.0, v10
	v_add_f32_e32 v11, 1.0, v11
	v_add_f32_e32 v170, 1.0, v170
	v_add_f32_e32 v171, 1.0, v171
	v_rcp_f32_e32 v10, v10
	v_rcp_f32_e32 v11, v11
	v_rcp_f32_e32 v170, v170
	v_rcp_f32_e32 v171, v171
	v_mul_f32_e32 v6, v6, v10
	v_mul_f32_e32 v7, v7, v11
	v_mul_f32_e32 v8, v8, v170
	v_mul_f32_e32 v9, v9, v171
	v_cvt_pk_bf16_f32 v10, v6, v7
	v_cvt_pk_bf16_f32 v11, v8, v9
	global_store_dwordx2 v194, v[10:11], s[12:13]
	s_add_u32 s30, s30, 0x8000000
	s_add_u32 s16, s60, s30
	s_addc_u32 s17, s61, 0
	s_add_u32 s18, s16, 0x4000
	s_addc_u32 s19, s17, 0
	global_store_dword v196, v126, s[16:17]
	global_store_dword v196, v128, s[16:17] offset:128
	global_store_dword v196, v127, s[18:19]
	global_store_dword v196, v129, s[18:19] offset:128
	s_waitcnt vmcnt(0) lgkmcnt(0)
